# attention: all 16 V fragment reads issued at the start of the QK block (one LDS burst, no mid-block lgkmcnt wait)
# speedup vs baseline: 1.0102x; 1.0053x over previous
.Latt_loop:
	s_waitcnt lgkmcnt(0)
	ds_read_b64_tr_b16 v[222:223], v134 offset:0
	ds_read_b64_tr_b16 v[224:225], v134 offset:2048
	ds_read_b64_tr_b16 v[226:227], v134 offset:4096
	ds_read_b64_tr_b16 v[228:229], v134 offset:6144
	ds_read_b64_tr_b16 v[230:231], v134 offset:8192
	ds_read_b64_tr_b16 v[232:233], v134 offset:10240
	ds_read_b64_tr_b16 v[234:235], v134 offset:12288
	ds_read_b64_tr_b16 v[236:237], v134 offset:14336
	ds_read_b64_tr_b16 v[238:239], v134 offset:512
	ds_read_b64_tr_b16 v[240:241], v134 offset:2560
	ds_read_b64_tr_b16 v[242:243], v134 offset:4608
	ds_read_b64_tr_b16 v[244:245], v134 offset:6656
	ds_read_b64_tr_b16 v[246:247], v134 offset:8704
	ds_read_b64_tr_b16 v[248:249], v134 offset:10752
	ds_read_b64_tr_b16 v[140:141], v134 offset:12800
	ds_read_b64_tr_b16 v[142:143], v134 offset:14848
	v_mfma_f32_32x32x16_bf16 v[190:205], v[156:159], v[86:89], 0
	v_exp_f32_e32 v48, v48
	v_add_f32_e32 v133, v133, v32
	v_exp_f32_e32 v49, v49
	v_add_f32_e32 v135, v135, v33
	v_exp_f32_e32 v50, v50
	v_mfma_f32_32x32x16_bf16 v[206:221], v[160:163], v[86:89], 0
	v_add_f32_e32 v133, v133, v34
	v_exp_f32_e32 v51, v51
	v_add_f32_e32 v135, v135, v35
	v_exp_f32_e32 v52, v52
	v_add_f32_e32 v133, v133, v36
	v_mfma_f32_32x32x16_bf16 v[190:205], v[164:167], v[82:85], v[190:205]
	v_exp_f32_e32 v53, v53
	v_add_f32_e32 v135, v135, v37
	v_exp_f32_e32 v54, v54
	v_add_f32_e32 v133, v133, v38
	v_exp_f32_e32 v55, v55
	v_add_f32_e32 v135, v135, v39
	v_mfma_f32_32x32x16_bf16 v[206:221], v[168:171], v[82:85], v[206:221]
	v_exp_f32_e32 v56, v56
	v_add_f32_e32 v133, v133, v40
	v_exp_f32_e32 v57, v57
	v_add_f32_e32 v135, v135, v41
	v_exp_f32_e32 v58, v58
	v_mfma_f32_32x32x16_bf16 v[190:205], v[172:175], v[90:93], v[190:205]
	v_add_f32_e32 v133, v133, v42
	v_exp_f32_e32 v59, v59
	v_add_f32_e32 v135, v135, v43
	v_exp_f32_e32 v60, v60
	v_add_f32_e32 v133, v133, v44
	v_mfma_f32_32x32x16_bf16 v[206:221], v[176:179], v[90:93], v[206:221]
	v_exp_f32_e32 v61, v61
	v_add_f32_e32 v135, v135, v45
	v_exp_f32_e32 v62, v62
	v_add_f32_e32 v133, v133, v46
	v_exp_f32_e32 v63, v63
	v_add_f32_e32 v135, v135, v47
	v_mfma_f32_32x32x16_bf16 v[190:205], v[180:183], v[94:97], v[190:205]
	v_add_f32_e32 v133, v133, v48
	v_add_f32_e32 v135, v135, v49
	v_add_f32_e32 v133, v133, v50
	v_add_f32_e32 v135, v135, v51
	v_add_f32_e32 v133, v133, v52
	v_mfma_f32_32x32x16_bf16 v[206:221], v[184:187], v[94:97], v[206:221]
	v_add_f32_e32 v135, v135, v53
	v_add_f32_e32 v133, v133, v54
	v_add_f32_e32 v135, v135, v55
	v_add_f32_e32 v133, v133, v56
	v_add_f32_e32 v135, v135, v57
	v_mfma_f32_32x32x16_bf16 v[190:205], v[64:67], v[98:101], v[190:205]
	v_add_f32_e32 v133, v133, v58
	v_add_f32_e32 v135, v135, v59
	v_add_f32_e32 v133, v133, v60
	v_add_f32_e32 v135, v135, v61
	v_add_f32_e32 v133, v133, v62
	v_add_f32_e32 v135, v135, v63
	v_mfma_f32_32x32x16_bf16 v[206:221], v[68:71], v[98:101], v[206:221]
	v_cvt_pk_bf16_f32 v32, v32, v33
	v_cvt_pk_bf16_f32 v33, v34, v35
	v_cvt_pk_bf16_f32 v34, v36, v37
	v_cvt_pk_bf16_f32 v35, v38, v39
	v_cvt_pk_bf16_f32 v36, v40, v41
	v_mfma_f32_32x32x16_bf16 v[190:205], v[72:75], v[102:105], v[190:205]
	v_cvt_pk_bf16_f32 v37, v42, v43
	v_cvt_pk_bf16_f32 v38, v44, v45
	v_cvt_pk_bf16_f32 v39, v46, v47
	v_cvt_pk_bf16_f32 v48, v48, v49
	v_cvt_pk_bf16_f32 v49, v50, v51
	v_mfma_f32_32x32x16_bf16 v[206:221], v[76:79], v[102:105], v[206:221]
	v_cvt_pk_bf16_f32 v50, v52, v53
	v_cvt_pk_bf16_f32 v51, v54, v55
	v_cvt_pk_bf16_f32 v52, v56, v57
	v_cvt_pk_bf16_f32 v53, v58, v59
	v_cvt_pk_bf16_f32 v54, v60, v61
	v_cvt_pk_bf16_f32 v55, v62, v63
	s_waitcnt vmcnt(3) lgkmcnt(0)
	s_barrier
	ds_read_b128 v[156:159], v146 offset:32768
	ds_read_b128 v[160:163], v146 offset:40960
	ds_read_b128 v[164:167], v147 offset:32768
	ds_read_b128 v[168:171], v147 offset:40960
	ds_read_b128 v[172:175], v148 offset:32768
	ds_read_b128 v[176:179], v148 offset:40960
	ds_read_b128 v[180:183], v149 offset:32768
	ds_read_b128 v[184:187], v149 offset:40960
	ds_read_b128 v[64:67], v150 offset:32768
	ds_read_b128 v[68:71], v150 offset:40960
	ds_read_b128 v[72:75], v151 offset:32768
	ds_read_b128 v[76:79], v151 offset:40960
	v_mfma_f32_32x32x16_bf16 v[0:15], v[32:35], v[222:225], v[0:15]
	s_add_i32 m0, s60, 0x4000
	v_exp_f32_e32 v190, v190
	v_exp_f32_e32 v191, v191
	v_mfma_f32_32x32x16_bf16 v[0:15], v[36:39], v[226:229], v[0:15]
	global_load_lds_dwordx4 v124, s[56:57]
	global_load_lds_dwordx4 v126, s[56:57] offset:1024
	v_exp_f32_e32 v192, v192
	v_exp_f32_e32 v193, v193
	v_mfma_f32_32x32x16_bf16 v[0:15], v[48:51], v[230:233], v[0:15]
	s_add_u32 s56, s56, 0x4000
	s_addc_u32 s57, s57, 0
	v_exp_f32_e32 v194, v194
	v_exp_f32_e32 v195, v195
	v_mfma_f32_32x32x16_bf16 v[0:15], v[52:55], v[234:237], v[0:15]
	s_add_i32 m0, s60, 0xc000
	v_exp_f32_e32 v196, v196
	v_exp_f32_e32 v197, v197
	v_mfma_f32_32x32x16_bf16 v[16:31], v[32:35], v[238:241], v[16:31]
	global_load_lds_dwordx4 v128, s[58:59]
	v_exp_f32_e32 v198, v198
	v_exp_f32_e32 v199, v199
	v_mfma_f32_32x32x16_bf16 v[16:31], v[36:39], v[242:245], v[16:31]
	s_add_u32 s58, s58, 0x2000
	s_addc_u32 s59, s59, 0
	v_exp_f32_e32 v200, v200
	v_exp_f32_e32 v201, v201
	v_mfma_f32_32x32x16_bf16 v[16:31], v[48:51], v[246:249], v[16:31]
	v_exp_f32_e32 v202, v202
	v_exp_f32_e32 v203, v203
	v_mfma_f32_32x32x16_bf16 v[16:31], v[52:55], v[140:143], v[16:31]
	v_exp_f32_e32 v204, v204
	v_exp_f32_e32 v205, v205
	s_waitcnt lgkmcnt(0)
	ds_read_b64_tr_b16 v[222:223], v134 offset:16384
	ds_read_b64_tr_b16 v[224:225], v134 offset:18432
	ds_read_b64_tr_b16 v[226:227], v134 offset:20480
	ds_read_b64_tr_b16 v[228:229], v134 offset:22528
	ds_read_b64_tr_b16 v[230:231], v134 offset:24576
	ds_read_b64_tr_b16 v[232:233], v134 offset:26624
	ds_read_b64_tr_b16 v[234:235], v134 offset:28672
	ds_read_b64_tr_b16 v[236:237], v134 offset:30720
	ds_read_b64_tr_b16 v[238:239], v134 offset:16896
	ds_read_b64_tr_b16 v[240:241], v134 offset:18944
	ds_read_b64_tr_b16 v[242:243], v134 offset:20992
	ds_read_b64_tr_b16 v[244:245], v134 offset:23040
	ds_read_b64_tr_b16 v[246:247], v134 offset:25088
	ds_read_b64_tr_b16 v[248:249], v134 offset:27136
	ds_read_b64_tr_b16 v[140:141], v134 offset:29184
	ds_read_b64_tr_b16 v[142:143], v134 offset:31232
	v_mfma_f32_32x32x16_bf16 v[32:47], v[156:159], v[86:89], 0
	v_exp_f32_e32 v206, v206
	v_add_f32_e32 v133, v133, v190
	v_exp_f32_e32 v207, v207
	v_add_f32_e32 v135, v135, v191
	v_exp_f32_e32 v208, v208
	v_mfma_f32_32x32x16_bf16 v[48:63], v[160:163], v[86:89], 0
	v_add_f32_e32 v133, v133, v192
	v_exp_f32_e32 v209, v209
	v_add_f32_e32 v135, v135, v193
	v_exp_f32_e32 v210, v210
	v_add_f32_e32 v133, v133, v194
	v_mfma_f32_32x32x16_bf16 v[32:47], v[164:167], v[82:85], v[32:47]
	v_exp_f32_e32 v211, v211
	v_add_f32_e32 v135, v135, v195
	v_exp_f32_e32 v212, v212
	v_add_f32_e32 v133, v133, v196
	v_exp_f32_e32 v213, v213
	v_add_f32_e32 v135, v135, v197
	v_mfma_f32_32x32x16_bf16 v[48:63], v[168:171], v[82:85], v[48:63]
	v_exp_f32_e32 v214, v214
	v_add_f32_e32 v133, v133, v198
	v_exp_f32_e32 v215, v215
	v_add_f32_e32 v135, v135, v199
	v_exp_f32_e32 v216, v216
	v_mfma_f32_32x32x16_bf16 v[32:47], v[172:175], v[90:93], v[32:47]
	v_add_f32_e32 v133, v133, v200
	v_exp_f32_e32 v217, v217
	v_add_f32_e32 v135, v135, v201
	v_exp_f32_e32 v218, v218
	v_add_f32_e32 v133, v133, v202
	v_mfma_f32_32x32x16_bf16 v[48:63], v[176:179], v[90:93], v[48:63]
	v_exp_f32_e32 v219, v219
	v_add_f32_e32 v135, v135, v203
	v_exp_f32_e32 v220, v220
	v_add_f32_e32 v133, v133, v204
	v_exp_f32_e32 v221, v221
	v_add_f32_e32 v135, v135, v205
	v_mfma_f32_32x32x16_bf16 v[32:47], v[180:183], v[94:97], v[32:47]
	v_add_f32_e32 v133, v133, v206
	v_add_f32_e32 v135, v135, v207
	v_add_f32_e32 v133, v133, v208
	v_add_f32_e32 v135, v135, v209
	v_add_f32_e32 v133, v133, v210
	v_mfma_f32_32x32x16_bf16 v[48:63], v[184:187], v[94:97], v[48:63]
	v_add_f32_e32 v135, v135, v211
	v_add_f32_e32 v133, v133, v212
	v_add_f32_e32 v135, v135, v213
	v_add_f32_e32 v133, v133, v214
	v_add_f32_e32 v135, v135, v215
	v_mfma_f32_32x32x16_bf16 v[32:47], v[64:67], v[98:101], v[32:47]
	v_add_f32_e32 v133, v133, v216
	v_add_f32_e32 v135, v135, v217
	v_add_f32_e32 v133, v133, v218
	v_add_f32_e32 v135, v135, v219
	v_add_f32_e32 v133, v133, v220
	v_add_f32_e32 v135, v135, v221
	v_mfma_f32_32x32x16_bf16 v[48:63], v[68:71], v[98:101], v[48:63]
	v_cvt_pk_bf16_f32 v190, v190, v191
	v_cvt_pk_bf16_f32 v191, v192, v193
	v_cvt_pk_bf16_f32 v192, v194, v195
	v_cvt_pk_bf16_f32 v193, v196, v197
	v_cvt_pk_bf16_f32 v194, v198, v199
	v_mfma_f32_32x32x16_bf16 v[32:47], v[72:75], v[102:105], v[32:47]
	v_cvt_pk_bf16_f32 v195, v200, v201
	v_cvt_pk_bf16_f32 v196, v202, v203
	v_cvt_pk_bf16_f32 v197, v204, v205
	v_cvt_pk_bf16_f32 v206, v206, v207
	v_cvt_pk_bf16_f32 v207, v208, v209
	v_mfma_f32_32x32x16_bf16 v[48:63], v[76:79], v[102:105], v[48:63]
	v_cvt_pk_bf16_f32 v208, v210, v211
	v_cvt_pk_bf16_f32 v209, v212, v213
	v_cvt_pk_bf16_f32 v210, v214, v215
	v_cvt_pk_bf16_f32 v211, v216, v217
	v_cvt_pk_bf16_f32 v212, v218, v219
	v_cvt_pk_bf16_f32 v213, v220, v221
	s_waitcnt vmcnt(3) lgkmcnt(0)
	s_barrier
	ds_read_b128 v[156:159], v146 offset:0
	ds_read_b128 v[160:163], v146 offset:8192
	ds_read_b128 v[164:167], v147 offset:0
	ds_read_b128 v[168:171], v147 offset:8192
	ds_read_b128 v[172:175], v148 offset:0
	ds_read_b128 v[176:179], v148 offset:8192
	ds_read_b128 v[180:183], v149 offset:0
	ds_read_b128 v[184:187], v149 offset:8192
	ds_read_b128 v[64:67], v150 offset:0
	ds_read_b128 v[68:71], v150 offset:8192
	ds_read_b128 v[72:75], v151 offset:0
	ds_read_b128 v[76:79], v151 offset:8192
	v_mfma_f32_32x32x16_bf16 v[0:15], v[190:193], v[222:225], v[0:15]
	s_add_i32 m0, s60, 0x8000
	v_exp_f32_e32 v32, v32
	v_exp_f32_e32 v33, v33
	v_mfma_f32_32x32x16_bf16 v[0:15], v[194:197], v[226:229], v[0:15]
	global_load_lds_dwordx4 v124, s[56:57]
	global_load_lds_dwordx4 v126, s[56:57] offset:1024
	v_exp_f32_e32 v34, v34
	v_exp_f32_e32 v35, v35
	v_mfma_f32_32x32x16_bf16 v[0:15], v[206:209], v[230:233], v[0:15]
	s_add_u32 s56, s56, 0x4000
	s_addc_u32 s57, s57, 0
	v_exp_f32_e32 v36, v36
	v_exp_f32_e32 v37, v37
	v_mfma_f32_32x32x16_bf16 v[0:15], v[210:213], v[234:237], v[0:15]
	s_add_i32 m0, s60, 0x10000
	v_exp_f32_e32 v38, v38
	v_exp_f32_e32 v39, v39
	v_mfma_f32_32x32x16_bf16 v[16:31], v[190:193], v[238:241], v[16:31]
	global_load_lds_dwordx4 v128, s[58:59]
	v_exp_f32_e32 v40, v40
	v_exp_f32_e32 v41, v41
	v_mfma_f32_32x32x16_bf16 v[16:31], v[194:197], v[242:245], v[16:31]
	s_add_u32 s58, s58, 0x2000
	s_addc_u32 s59, s59, 0
	v_exp_f32_e32 v42, v42
	v_exp_f32_e32 v43, v43
	v_mfma_f32_32x32x16_bf16 v[16:31], v[206:209], v[246:249], v[16:31]
	v_exp_f32_e32 v44, v44
	v_exp_f32_e32 v45, v45
	v_mfma_f32_32x32x16_bf16 v[16:31], v[210:213], v[140:143], v[16:31]
	v_exp_f32_e32 v46, v46
	v_exp_f32_e32 v47, v47
	s_waitcnt lgkmcnt(0)
	ds_read_b64_tr_b16 v[222:223], v134 offset:32768
	ds_read_b64_tr_b16 v[224:225], v134 offset:34816
	ds_read_b64_tr_b16 v[226:227], v134 offset:36864
	ds_read_b64_tr_b16 v[228:229], v134 offset:38912
	ds_read_b64_tr_b16 v[230:231], v134 offset:40960
	ds_read_b64_tr_b16 v[232:233], v134 offset:43008
	ds_read_b64_tr_b16 v[234:235], v134 offset:45056
	ds_read_b64_tr_b16 v[236:237], v134 offset:47104
	ds_read_b64_tr_b16 v[238:239], v134 offset:33280
	ds_read_b64_tr_b16 v[240:241], v134 offset:35328
	ds_read_b64_tr_b16 v[242:243], v134 offset:37376
	ds_read_b64_tr_b16 v[244:245], v134 offset:39424
	ds_read_b64_tr_b16 v[246:247], v134 offset:41472
	ds_read_b64_tr_b16 v[248:249], v134 offset:43520
	ds_read_b64_tr_b16 v[140:141], v134 offset:45568
	ds_read_b64_tr_b16 v[142:143], v134 offset:47616
	v_mfma_f32_32x32x16_bf16 v[190:205], v[156:159], v[86:89], 0
	v_exp_f32_e32 v48, v48
	v_add_f32_e32 v133, v133, v32
	v_exp_f32_e32 v49, v49
	v_add_f32_e32 v135, v135, v33
	v_exp_f32_e32 v50, v50
	v_mfma_f32_32x32x16_bf16 v[206:221], v[160:163], v[86:89], 0
	v_add_f32_e32 v133, v133, v34
	v_exp_f32_e32 v51, v51
	v_add_f32_e32 v135, v135, v35
	v_exp_f32_e32 v52, v52
	v_add_f32_e32 v133, v133, v36
	v_mfma_f32_32x32x16_bf16 v[190:205], v[164:167], v[82:85], v[190:205]
	v_exp_f32_e32 v53, v53
	v_add_f32_e32 v135, v135, v37
	v_exp_f32_e32 v54, v54
	v_add_f32_e32 v133, v133, v38
	v_exp_f32_e32 v55, v55
	v_add_f32_e32 v135, v135, v39
	v_mfma_f32_32x32x16_bf16 v[206:221], v[168:171], v[82:85], v[206:221]
	v_exp_f32_e32 v56, v56
	v_add_f32_e32 v133, v133, v40
	v_exp_f32_e32 v57, v57
	v_add_f32_e32 v135, v135, v41
	v_exp_f32_e32 v58, v58
	v_mfma_f32_32x32x16_bf16 v[190:205], v[172:175], v[90:93], v[190:205]
	v_add_f32_e32 v133, v133, v42
	v_exp_f32_e32 v59, v59
	v_add_f32_e32 v135, v135, v43
	v_exp_f32_e32 v60, v60
	v_add_f32_e32 v133, v133, v44
	v_mfma_f32_32x32x16_bf16 v[206:221], v[176:179], v[90:93], v[206:221]
	v_exp_f32_e32 v61, v61
	v_add_f32_e32 v135, v135, v45
	v_exp_f32_e32 v62, v62
	v_add_f32_e32 v133, v133, v46
	v_exp_f32_e32 v63, v63
	v_add_f32_e32 v135, v135, v47
	v_mfma_f32_32x32x16_bf16 v[190:205], v[180:183], v[94:97], v[190:205]
	v_add_f32_e32 v133, v133, v48
	v_add_f32_e32 v135, v135, v49
	v_add_f32_e32 v133, v133, v50
	v_add_f32_e32 v135, v135, v51
	v_add_f32_e32 v133, v133, v52
	v_mfma_f32_32x32x16_bf16 v[206:221], v[184:187], v[94:97], v[206:221]
	v_add_f32_e32 v135, v135, v53
	v_add_f32_e32 v133, v133, v54
	v_add_f32_e32 v135, v135, v55
	v_add_f32_e32 v133, v133, v56
	v_add_f32_e32 v135, v135, v57
	v_mfma_f32_32x32x16_bf16 v[190:205], v[64:67], v[98:101], v[190:205]
	v_add_f32_e32 v133, v133, v58
	v_add_f32_e32 v135, v135, v59
	v_add_f32_e32 v133, v133, v60
	v_add_f32_e32 v135, v135, v61
	v_add_f32_e32 v133, v133, v62
	v_add_f32_e32 v135, v135, v63
	v_mfma_f32_32x32x16_bf16 v[206:221], v[68:71], v[98:101], v[206:221]
	v_cvt_pk_bf16_f32 v32, v32, v33
	v_cvt_pk_bf16_f32 v33, v34, v35
	v_cvt_pk_bf16_f32 v34, v36, v37
	v_cvt_pk_bf16_f32 v35, v38, v39
	v_cvt_pk_bf16_f32 v36, v40, v41
	v_mfma_f32_32x32x16_bf16 v[190:205], v[72:75], v[102:105], v[190:205]
	v_cvt_pk_bf16_f32 v37, v42, v43
	v_cvt_pk_bf16_f32 v38, v44, v45
	v_cvt_pk_bf16_f32 v39, v46, v47
	v_cvt_pk_bf16_f32 v48, v48, v49
	v_cvt_pk_bf16_f32 v49, v50, v51
	v_mfma_f32_32x32x16_bf16 v[206:221], v[76:79], v[102:105], v[206:221]
	v_cvt_pk_bf16_f32 v50, v52, v53
	v_cvt_pk_bf16_f32 v51, v54, v55
	v_cvt_pk_bf16_f32 v52, v56, v57
	v_cvt_pk_bf16_f32 v53, v58, v59
	v_cvt_pk_bf16_f32 v54, v60, v61
	v_cvt_pk_bf16_f32 v55, v62, v63
	s_waitcnt vmcnt(3) lgkmcnt(0)
	s_barrier
	ds_read_b128 v[156:159], v146 offset:16384
	ds_read_b128 v[160:163], v146 offset:24576
	ds_read_b128 v[164:167], v147 offset:16384
	ds_read_b128 v[168:171], v147 offset:24576
	ds_read_b128 v[172:175], v148 offset:16384
	ds_read_b128 v[176:179], v148 offset:24576
	ds_read_b128 v[180:183], v149 offset:16384
	ds_read_b128 v[184:187], v149 offset:24576
	ds_read_b128 v[64:67], v150 offset:16384
	ds_read_b128 v[68:71], v150 offset:24576
	ds_read_b128 v[72:75], v151 offset:16384
	ds_read_b128 v[76:79], v151 offset:24576
	v_mfma_f32_32x32x16_bf16 v[0:15], v[32:35], v[222:225], v[0:15]
	s_add_i32 m0, s60, 0x0
	v_exp_f32_e32 v190, v190
	v_exp_f32_e32 v191, v191
	v_mfma_f32_32x32x16_bf16 v[0:15], v[36:39], v[226:229], v[0:15]
	global_load_lds_dwordx4 v124, s[56:57]
	global_load_lds_dwordx4 v126, s[56:57] offset:1024
	v_exp_f32_e32 v192, v192
	v_exp_f32_e32 v193, v193
	v_mfma_f32_32x32x16_bf16 v[0:15], v[48:51], v[230:233], v[0:15]
	s_add_u32 s56, s56, 0x4000
	s_addc_u32 s57, s57, 0
	v_exp_f32_e32 v194, v194
	v_exp_f32_e32 v195, v195
	v_mfma_f32_32x32x16_bf16 v[0:15], v[52:55], v[234:237], v[0:15]
	s_add_i32 m0, s60, 0x14000
	v_exp_f32_e32 v196, v196
	v_exp_f32_e32 v197, v197
	v_mfma_f32_32x32x16_bf16 v[16:31], v[32:35], v[238:241], v[16:31]
	global_load_lds_dwordx4 v128, s[58:59]
	v_exp_f32_e32 v198, v198
	v_exp_f32_e32 v199, v199
	v_mfma_f32_32x32x16_bf16 v[16:31], v[36:39], v[242:245], v[16:31]
	s_add_u32 s58, s58, 0x2000
	s_addc_u32 s59, s59, 0
	v_exp_f32_e32 v200, v200
	v_exp_f32_e32 v201, v201
	v_mfma_f32_32x32x16_bf16 v[16:31], v[48:51], v[246:249], v[16:31]
	v_exp_f32_e32 v202, v202
	v_exp_f32_e32 v203, v203
	v_mfma_f32_32x32x16_bf16 v[16:31], v[52:55], v[140:143], v[16:31]
	v_exp_f32_e32 v204, v204
	v_exp_f32_e32 v205, v205
	s_waitcnt lgkmcnt(0)
	ds_read_b64_tr_b16 v[222:223], v134 offset:0
	ds_read_b64_tr_b16 v[224:225], v134 offset:2048
	ds_read_b64_tr_b16 v[226:227], v134 offset:4096
	ds_read_b64_tr_b16 v[228:229], v134 offset:6144
	ds_read_b64_tr_b16 v[230:231], v134 offset:8192
	ds_read_b64_tr_b16 v[232:233], v134 offset:10240
	ds_read_b64_tr_b16 v[234:235], v134 offset:12288
	ds_read_b64_tr_b16 v[236:237], v134 offset:14336
	ds_read_b64_tr_b16 v[238:239], v134 offset:512
	ds_read_b64_tr_b16 v[240:241], v134 offset:2560
	ds_read_b64_tr_b16 v[242:243], v134 offset:4608
	ds_read_b64_tr_b16 v[244:245], v134 offset:6656
	ds_read_b64_tr_b16 v[246:247], v134 offset:8704
	ds_read_b64_tr_b16 v[248:249], v134 offset:10752
	ds_read_b64_tr_b16 v[140:141], v134 offset:12800
	ds_read_b64_tr_b16 v[142:143], v134 offset:14848
	v_mfma_f32_32x32x16_bf16 v[32:47], v[156:159], v[86:89], 0
	v_exp_f32_e32 v206, v206
	v_add_f32_e32 v133, v133, v190
	v_exp_f32_e32 v207, v207
	v_add_f32_e32 v135, v135, v191
	v_exp_f32_e32 v208, v208
	v_mfma_f32_32x32x16_bf16 v[48:63], v[160:163], v[86:89], 0
	v_add_f32_e32 v133, v133, v192
	v_exp_f32_e32 v209, v209
	v_add_f32_e32 v135, v135, v193
	v_exp_f32_e32 v210, v210
	v_add_f32_e32 v133, v133, v194
	v_mfma_f32_32x32x16_bf16 v[32:47], v[164:167], v[82:85], v[32:47]
	v_exp_f32_e32 v211, v211
	v_add_f32_e32 v135, v135, v195
	v_exp_f32_e32 v212, v212
	v_add_f32_e32 v133, v133, v196
	v_exp_f32_e32 v213, v213
	v_add_f32_e32 v135, v135, v197
	v_mfma_f32_32x32x16_bf16 v[48:63], v[168:171], v[82:85], v[48:63]
	v_exp_f32_e32 v214, v214
	v_add_f32_e32 v133, v133, v198
	v_exp_f32_e32 v215, v215
	v_add_f32_e32 v135, v135, v199
	v_exp_f32_e32 v216, v216
	v_mfma_f32_32x32x16_bf16 v[32:47], v[172:175], v[90:93], v[32:47]
	v_add_f32_e32 v133, v133, v200
	v_exp_f32_e32 v217, v217
	v_add_f32_e32 v135, v135, v201
	v_exp_f32_e32 v218, v218
	v_add_f32_e32 v133, v133, v202
	v_mfma_f32_32x32x16_bf16 v[48:63], v[176:179], v[90:93], v[48:63]
	v_exp_f32_e32 v219, v219
	v_add_f32_e32 v135, v135, v203
	v_exp_f32_e32 v220, v220
	v_add_f32_e32 v133, v133, v204
	v_exp_f32_e32 v221, v221
	v_add_f32_e32 v135, v135, v205
	v_mfma_f32_32x32x16_bf16 v[32:47], v[180:183], v[94:97], v[32:47]
	v_add_f32_e32 v133, v133, v206
	v_add_f32_e32 v135, v135, v207
	v_add_f32_e32 v133, v133, v208
	v_add_f32_e32 v135, v135, v209
	v_add_f32_e32 v133, v133, v210
	v_mfma_f32_32x32x16_bf16 v[48:63], v[184:187], v[94:97], v[48:63]
	v_add_f32_e32 v135, v135, v211
	v_add_f32_e32 v133, v133, v212
	v_add_f32_e32 v135, v135, v213
	v_add_f32_e32 v133, v133, v214
	v_add_f32_e32 v135, v135, v215
	v_mfma_f32_32x32x16_bf16 v[32:47], v[64:67], v[98:101], v[32:47]
	v_add_f32_e32 v133, v133, v216
	v_add_f32_e32 v135, v135, v217
	v_add_f32_e32 v133, v133, v218
	v_add_f32_e32 v135, v135, v219
	v_add_f32_e32 v133, v133, v220
	v_add_f32_e32 v135, v135, v221
	v_mfma_f32_32x32x16_bf16 v[48:63], v[68:71], v[98:101], v[48:63]
	v_cvt_pk_bf16_f32 v190, v190, v191
	v_cvt_pk_bf16_f32 v191, v192, v193
	v_cvt_pk_bf16_f32 v192, v194, v195
	v_cvt_pk_bf16_f32 v193, v196, v197
	v_cvt_pk_bf16_f32 v194, v198, v199
	v_mfma_f32_32x32x16_bf16 v[32:47], v[72:75], v[102:105], v[32:47]
	v_cvt_pk_bf16_f32 v195, v200, v201
	v_cvt_pk_bf16_f32 v196, v202, v203
	v_cvt_pk_bf16_f32 v197, v204, v205
	v_cvt_pk_bf16_f32 v206, v206, v207
	v_cvt_pk_bf16_f32 v207, v208, v209
	v_mfma_f32_32x32x16_bf16 v[48:63], v[76:79], v[102:105], v[48:63]
	v_cvt_pk_bf16_f32 v208, v210, v211
	v_cvt_pk_bf16_f32 v209, v212, v213
	v_cvt_pk_bf16_f32 v210, v214, v215
	v_cvt_pk_bf16_f32 v211, v216, v217
	v_cvt_pk_bf16_f32 v212, v218, v219
	v_cvt_pk_bf16_f32 v213, v220, v221
	s_waitcnt vmcnt(3) lgkmcnt(0)
	s_barrier
	ds_read_b128 v[156:159], v146 offset:32768
	ds_read_b128 v[160:163], v146 offset:40960
	ds_read_b128 v[164:167], v147 offset:32768
	ds_read_b128 v[168:171], v147 offset:40960
	ds_read_b128 v[172:175], v148 offset:32768
	ds_read_b128 v[176:179], v148 offset:40960
	ds_read_b128 v[180:183], v149 offset:32768
	ds_read_b128 v[184:187], v149 offset:40960
	ds_read_b128 v[64:67], v150 offset:32768
	ds_read_b128 v[68:71], v150 offset:40960
	ds_read_b128 v[72:75], v151 offset:32768
	ds_read_b128 v[76:79], v151 offset:40960
	v_mfma_f32_32x32x16_bf16 v[0:15], v[190:193], v[222:225], v[0:15]
	s_add_i32 m0, s60, 0x4000
	v_exp_f32_e32 v32, v32
	v_exp_f32_e32 v33, v33
	v_mfma_f32_32x32x16_bf16 v[0:15], v[194:197], v[226:229], v[0:15]
	global_load_lds_dwordx4 v124, s[56:57]
	global_load_lds_dwordx4 v126, s[56:57] offset:1024
	v_exp_f32_e32 v34, v34
	v_exp_f32_e32 v35, v35
	v_mfma_f32_32x32x16_bf16 v[0:15], v[206:209], v[230:233], v[0:15]
	s_add_u32 s56, s56, 0x4000
	s_addc_u32 s57, s57, 0
	v_exp_f32_e32 v36, v36
	v_exp_f32_e32 v37, v37
	v_mfma_f32_32x32x16_bf16 v[0:15], v[210:213], v[234:237], v[0:15]
	s_add_i32 m0, s60, 0xc000
	v_exp_f32_e32 v38, v38
	v_exp_f32_e32 v39, v39
	v_mfma_f32_32x32x16_bf16 v[16:31], v[190:193], v[238:241], v[16:31]
	global_load_lds_dwordx4 v128, s[58:59]
	v_exp_f32_e32 v40, v40
	v_exp_f32_e32 v41, v41
	v_mfma_f32_32x32x16_bf16 v[16:31], v[194:197], v[242:245], v[16:31]
	s_add_u32 s58, s58, 0x2000
	s_addc_u32 s59, s59, 0
	v_exp_f32_e32 v42, v42
	v_exp_f32_e32 v43, v43
	v_mfma_f32_32x32x16_bf16 v[16:31], v[206:209], v[246:249], v[16:31]
	v_exp_f32_e32 v44, v44
	v_exp_f32_e32 v45, v45
	v_mfma_f32_32x32x16_bf16 v[16:31], v[210:213], v[140:143], v[16:31]
	v_exp_f32_e32 v46, v46
	v_exp_f32_e32 v47, v47
	s_waitcnt lgkmcnt(0)
	ds_read_b64_tr_b16 v[222:223], v134 offset:16384
	ds_read_b64_tr_b16 v[224:225], v134 offset:18432
	ds_read_b64_tr_b16 v[226:227], v134 offset:20480
	ds_read_b64_tr_b16 v[228:229], v134 offset:22528
	ds_read_b64_tr_b16 v[230:231], v134 offset:24576
	ds_read_b64_tr_b16 v[232:233], v134 offset:26624
	ds_read_b64_tr_b16 v[234:235], v134 offset:28672
	ds_read_b64_tr_b16 v[236:237], v134 offset:30720
	ds_read_b64_tr_b16 v[238:239], v134 offset:16896
	ds_read_b64_tr_b16 v[240:241], v134 offset:18944
	ds_read_b64_tr_b16 v[242:243], v134 offset:20992
	ds_read_b64_tr_b16 v[244:245], v134 offset:23040
	ds_read_b64_tr_b16 v[246:247], v134 offset:25088
	ds_read_b64_tr_b16 v[248:249], v134 offset:27136
	ds_read_b64_tr_b16 v[140:141], v134 offset:29184
	ds_read_b64_tr_b16 v[142:143], v134 offset:31232
	v_mfma_f32_32x32x16_bf16 v[190:205], v[156:159], v[86:89], 0
	v_exp_f32_e32 v48, v48
	v_add_f32_e32 v133, v133, v32
	v_exp_f32_e32 v49, v49
	v_add_f32_e32 v135, v135, v33
	v_exp_f32_e32 v50, v50
	v_mfma_f32_32x32x16_bf16 v[206:221], v[160:163], v[86:89], 0
	v_add_f32_e32 v133, v133, v34
	v_exp_f32_e32 v51, v51
	v_add_f32_e32 v135, v135, v35
	v_exp_f32_e32 v52, v52
	v_add_f32_e32 v133, v133, v36
	v_mfma_f32_32x32x16_bf16 v[190:205], v[164:167], v[82:85], v[190:205]
	v_exp_f32_e32 v53, v53
	v_add_f32_e32 v135, v135, v37
	v_exp_f32_e32 v54, v54
	v_add_f32_e32 v133, v133, v38
	v_exp_f32_e32 v55, v55
	v_add_f32_e32 v135, v135, v39
	v_mfma_f32_32x32x16_bf16 v[206:221], v[168:171], v[82:85], v[206:221]
	v_exp_f32_e32 v56, v56
	v_add_f32_e32 v133, v133, v40
	v_exp_f32_e32 v57, v57
	v_add_f32_e32 v135, v135, v41
	v_exp_f32_e32 v58, v58
	v_mfma_f32_32x32x16_bf16 v[190:205], v[172:175], v[90:93], v[190:205]
	v_add_f32_e32 v133, v133, v42
	v_exp_f32_e32 v59, v59
	v_add_f32_e32 v135, v135, v43
	v_exp_f32_e32 v60, v60
	v_add_f32_e32 v133, v133, v44
	v_mfma_f32_32x32x16_bf16 v[206:221], v[176:179], v[90:93], v[206:221]
	v_exp_f32_e32 v61, v61
	v_add_f32_e32 v135, v135, v45
	v_exp_f32_e32 v62, v62
	v_add_f32_e32 v133, v133, v46
	v_exp_f32_e32 v63, v63
	v_add_f32_e32 v135, v135, v47
	v_mfma_f32_32x32x16_bf16 v[190:205], v[180:183], v[94:97], v[190:205]
	v_add_f32_e32 v133, v133, v48
	v_add_f32_e32 v135, v135, v49
	v_add_f32_e32 v133, v133, v50
	v_add_f32_e32 v135, v135, v51
	v_add_f32_e32 v133, v133, v52
	v_mfma_f32_32x32x16_bf16 v[206:221], v[184:187], v[94:97], v[206:221]
	v_add_f32_e32 v135, v135, v53
	v_add_f32_e32 v133, v133, v54
	v_add_f32_e32 v135, v135, v55
	v_add_f32_e32 v133, v133, v56
	v_add_f32_e32 v135, v135, v57
	v_mfma_f32_32x32x16_bf16 v[190:205], v[64:67], v[98:101], v[190:205]
	v_add_f32_e32 v133, v133, v58
	v_add_f32_e32 v135, v135, v59
	v_add_f32_e32 v133, v133, v60
	v_add_f32_e32 v135, v135, v61
	v_add_f32_e32 v133, v133, v62
	v_add_f32_e32 v135, v135, v63
	v_mfma_f32_32x32x16_bf16 v[206:221], v[68:71], v[98:101], v[206:221]
	v_cvt_pk_bf16_f32 v32, v32, v33
	v_cvt_pk_bf16_f32 v33, v34, v35
	v_cvt_pk_bf16_f32 v34, v36, v37
	v_cvt_pk_bf16_f32 v35, v38, v39
	v_cvt_pk_bf16_f32 v36, v40, v41
	v_mfma_f32_32x32x16_bf16 v[190:205], v[72:75], v[102:105], v[190:205]
	v_cvt_pk_bf16_f32 v37, v42, v43
	v_cvt_pk_bf16_f32 v38, v44, v45
	v_cvt_pk_bf16_f32 v39, v46, v47
	v_cvt_pk_bf16_f32 v48, v48, v49
	v_cvt_pk_bf16_f32 v49, v50, v51
	v_mfma_f32_32x32x16_bf16 v[206:221], v[76:79], v[102:105], v[206:221]
	v_cvt_pk_bf16_f32 v50, v52, v53
	v_cvt_pk_bf16_f32 v51, v54, v55
	v_cvt_pk_bf16_f32 v52, v56, v57
	v_cvt_pk_bf16_f32 v53, v58, v59
	v_cvt_pk_bf16_f32 v54, v60, v61
	v_cvt_pk_bf16_f32 v55, v62, v63
	s_waitcnt vmcnt(3) lgkmcnt(0)
	s_barrier
	ds_read_b128 v[156:159], v146 offset:0
	ds_read_b128 v[160:163], v146 offset:8192
	ds_read_b128 v[164:167], v147 offset:0
	ds_read_b128 v[168:171], v147 offset:8192
	ds_read_b128 v[172:175], v148 offset:0
	ds_read_b128 v[176:179], v148 offset:8192
	ds_read_b128 v[180:183], v149 offset:0
	ds_read_b128 v[184:187], v149 offset:8192
	ds_read_b128 v[64:67], v150 offset:0
	ds_read_b128 v[68:71], v150 offset:8192
	ds_read_b128 v[72:75], v151 offset:0
	ds_read_b128 v[76:79], v151 offset:8192
	v_mfma_f32_32x32x16_bf16 v[0:15], v[32:35], v[222:225], v[0:15]
	s_add_i32 m0, s60, 0x8000
	v_exp_f32_e32 v190, v190
	v_exp_f32_e32 v191, v191
	v_mfma_f32_32x32x16_bf16 v[0:15], v[36:39], v[226:229], v[0:15]
	global_load_lds_dwordx4 v124, s[56:57]
	global_load_lds_dwordx4 v126, s[56:57] offset:1024
	v_exp_f32_e32 v192, v192
	v_exp_f32_e32 v193, v193
	v_mfma_f32_32x32x16_bf16 v[0:15], v[48:51], v[230:233], v[0:15]
	s_add_u32 s56, s56, 0x4000
	s_addc_u32 s57, s57, 0
	v_exp_f32_e32 v194, v194
	v_exp_f32_e32 v195, v195
	v_mfma_f32_32x32x16_bf16 v[0:15], v[52:55], v[234:237], v[0:15]
	s_add_i32 m0, s60, 0x10000
	v_exp_f32_e32 v196, v196
	v_exp_f32_e32 v197, v197
	v_mfma_f32_32x32x16_bf16 v[16:31], v[32:35], v[238:241], v[16:31]
	global_load_lds_dwordx4 v128, s[58:59]
	v_exp_f32_e32 v198, v198
	v_exp_f32_e32 v199, v199
	v_mfma_f32_32x32x16_bf16 v[16:31], v[36:39], v[242:245], v[16:31]
	s_add_u32 s58, s58, 0x2000
	s_addc_u32 s59, s59, 0
	v_exp_f32_e32 v200, v200
	v_exp_f32_e32 v201, v201
	v_mfma_f32_32x32x16_bf16 v[16:31], v[48:51], v[246:249], v[16:31]
	v_exp_f32_e32 v202, v202
	v_exp_f32_e32 v203, v203
	v_mfma_f32_32x32x16_bf16 v[16:31], v[52:55], v[140:143], v[16:31]
	v_exp_f32_e32 v204, v204
	v_exp_f32_e32 v205, v205
	s_waitcnt lgkmcnt(0)
	ds_read_b64_tr_b16 v[222:223], v134 offset:32768
	ds_read_b64_tr_b16 v[224:225], v134 offset:34816
	ds_read_b64_tr_b16 v[226:227], v134 offset:36864
	ds_read_b64_tr_b16 v[228:229], v134 offset:38912
	ds_read_b64_tr_b16 v[230:231], v134 offset:40960
	ds_read_b64_tr_b16 v[232:233], v134 offset:43008
	ds_read_b64_tr_b16 v[234:235], v134 offset:45056
	ds_read_b64_tr_b16 v[236:237], v134 offset:47104
	ds_read_b64_tr_b16 v[238:239], v134 offset:33280
	ds_read_b64_tr_b16 v[240:241], v134 offset:35328
	ds_read_b64_tr_b16 v[242:243], v134 offset:37376
	ds_read_b64_tr_b16 v[244:245], v134 offset:39424
	ds_read_b64_tr_b16 v[246:247], v134 offset:41472
	ds_read_b64_tr_b16 v[248:249], v134 offset:43520
	ds_read_b64_tr_b16 v[140:141], v134 offset:45568
	ds_read_b64_tr_b16 v[142:143], v134 offset:47616
	v_mfma_f32_32x32x16_bf16 v[32:47], v[156:159], v[86:89], 0
	v_exp_f32_e32 v206, v206
	v_add_f32_e32 v133, v133, v190
	v_exp_f32_e32 v207, v207
	v_add_f32_e32 v135, v135, v191
	v_exp_f32_e32 v208, v208
	v_mfma_f32_32x32x16_bf16 v[48:63], v[160:163], v[86:89], 0
	v_add_f32_e32 v133, v133, v192
	v_exp_f32_e32 v209, v209
	v_add_f32_e32 v135, v135, v193
	v_exp_f32_e32 v210, v210
	v_add_f32_e32 v133, v133, v194
	v_mfma_f32_32x32x16_bf16 v[32:47], v[164:167], v[82:85], v[32:47]
	v_exp_f32_e32 v211, v211
	v_add_f32_e32 v135, v135, v195
	v_exp_f32_e32 v212, v212
	v_add_f32_e32 v133, v133, v196
	v_exp_f32_e32 v213, v213
	v_add_f32_e32 v135, v135, v197
	v_mfma_f32_32x32x16_bf16 v[48:63], v[168:171], v[82:85], v[48:63]
	v_exp_f32_e32 v214, v214
	v_add_f32_e32 v133, v133, v198
	v_exp_f32_e32 v215, v215
	v_add_f32_e32 v135, v135, v199
	v_exp_f32_e32 v216, v216
	v_mfma_f32_32x32x16_bf16 v[32:47], v[172:175], v[90:93], v[32:47]
	v_add_f32_e32 v133, v133, v200
	v_exp_f32_e32 v217, v217
	v_add_f32_e32 v135, v135, v201
	v_exp_f32_e32 v218, v218
	v_add_f32_e32 v133, v133, v202
	v_mfma_f32_32x32x16_bf16 v[48:63], v[176:179], v[90:93], v[48:63]
	v_exp_f32_e32 v219, v219
	v_add_f32_e32 v135, v135, v203
	v_exp_f32_e32 v220, v220
	v_add_f32_e32 v133, v133, v204
	v_exp_f32_e32 v221, v221
	v_add_f32_e32 v135, v135, v205
	v_mfma_f32_32x32x16_bf16 v[32:47], v[180:183], v[94:97], v[32:47]
	v_add_f32_e32 v133, v133, v206
	v_add_f32_e32 v135, v135, v207
	v_add_f32_e32 v133, v133, v208
	v_add_f32_e32 v135, v135, v209
	v_add_f32_e32 v133, v133, v210
	v_mfma_f32_32x32x16_bf16 v[48:63], v[184:187], v[94:97], v[48:63]
	v_add_f32_e32 v135, v135, v211
	v_add_f32_e32 v133, v133, v212
	v_add_f32_e32 v135, v135, v213
	v_add_f32_e32 v133, v133, v214
	v_add_f32_e32 v135, v135, v215
	v_mfma_f32_32x32x16_bf16 v[32:47], v[64:67], v[98:101], v[32:47]
	v_add_f32_e32 v133, v133, v216
	v_add_f32_e32 v135, v135, v217
	v_add_f32_e32 v133, v133, v218
	v_add_f32_e32 v135, v135, v219
	v_add_f32_e32 v133, v133, v220
	v_add_f32_e32 v135, v135, v221
	v_mfma_f32_32x32x16_bf16 v[48:63], v[68:71], v[98:101], v[48:63]
	v_cvt_pk_bf16_f32 v190, v190, v191
	v_cvt_pk_bf16_f32 v191, v192, v193
	v_cvt_pk_bf16_f32 v192, v194, v195
	v_cvt_pk_bf16_f32 v193, v196, v197
	v_cvt_pk_bf16_f32 v194, v198, v199
	v_mfma_f32_32x32x16_bf16 v[32:47], v[72:75], v[102:105], v[32:47]
	v_cvt_pk_bf16_f32 v195, v200, v201
	v_cvt_pk_bf16_f32 v196, v202, v203
	v_cvt_pk_bf16_f32 v197, v204, v205
	v_cvt_pk_bf16_f32 v206, v206, v207
	v_cvt_pk_bf16_f32 v207, v208, v209
	v_mfma_f32_32x32x16_bf16 v[48:63], v[76:79], v[102:105], v[48:63]
	v_cvt_pk_bf16_f32 v208, v210, v211
	v_cvt_pk_bf16_f32 v209, v212, v213
	v_cvt_pk_bf16_f32 v210, v214, v215
	v_cvt_pk_bf16_f32 v211, v216, v217
	v_cvt_pk_bf16_f32 v212, v218, v219
	v_cvt_pk_bf16_f32 v213, v220, v221
	s_waitcnt vmcnt(3) lgkmcnt(0)
	s_barrier
	ds_read_b128 v[156:159], v146 offset:16384
	ds_read_b128 v[160:163], v146 offset:24576
	ds_read_b128 v[164:167], v147 offset:16384
	ds_read_b128 v[168:171], v147 offset:24576
	ds_read_b128 v[172:175], v148 offset:16384
	ds_read_b128 v[176:179], v148 offset:24576
	ds_read_b128 v[180:183], v149 offset:16384
	ds_read_b128 v[184:187], v149 offset:24576
	ds_read_b128 v[64:67], v150 offset:16384
	ds_read_b128 v[68:71], v150 offset:24576
	ds_read_b128 v[72:75], v151 offset:16384
	ds_read_b128 v[76:79], v151 offset:24576
	v_mfma_f32_32x32x16_bf16 v[0:15], v[190:193], v[222:225], v[0:15]
	s_add_i32 m0, s60, 0x0
	v_exp_f32_e32 v32, v32
	v_exp_f32_e32 v33, v33
	v_mfma_f32_32x32x16_bf16 v[0:15], v[194:197], v[226:229], v[0:15]
	global_load_lds_dwordx4 v124, s[56:57]
	global_load_lds_dwordx4 v126, s[56:57] offset:1024
	v_exp_f32_e32 v34, v34
	v_exp_f32_e32 v35, v35
	v_mfma_f32_32x32x16_bf16 v[0:15], v[206:209], v[230:233], v[0:15]
	s_add_u32 s56, s56, 0x4000
	s_addc_u32 s57, s57, 0
	v_exp_f32_e32 v36, v36
	v_exp_f32_e32 v37, v37
	v_mfma_f32_32x32x16_bf16 v[0:15], v[210:213], v[234:237], v[0:15]
	s_add_i32 m0, s60, 0x14000
	v_exp_f32_e32 v38, v38
	v_exp_f32_e32 v39, v39
	v_mfma_f32_32x32x16_bf16 v[16:31], v[190:193], v[238:241], v[16:31]
	global_load_lds_dwordx4 v128, s[58:59]
	v_exp_f32_e32 v40, v40
	v_exp_f32_e32 v41, v41
	v_mfma_f32_32x32x16_bf16 v[16:31], v[194:197], v[242:245], v[16:31]
	s_add_u32 s58, s58, 0x2000
	s_addc_u32 s59, s59, 0
	v_exp_f32_e32 v42, v42
	v_exp_f32_e32 v43, v43
	v_mfma_f32_32x32x16_bf16 v[16:31], v[206:209], v[246:249], v[16:31]
	v_exp_f32_e32 v44, v44
	v_exp_f32_e32 v45, v45
	v_mfma_f32_32x32x16_bf16 v[16:31], v[210:213], v[140:143], v[16:31]
	v_exp_f32_e32 v46, v46
	v_exp_f32_e32 v47, v47
	s_sub_u32 s33, s33, 1
	s_cmp_lg_u32 s33, 0
	s_cbranch_scc1 .Latt_loop
	s_waitcnt lgkmcnt(0)
	ds_read_b64_tr_b16 v[222:223], v134 offset:0
	ds_read_b64_tr_b16 v[224:225], v134 offset:2048
	ds_read_b64_tr_b16 v[226:227], v134 offset:4096
	ds_read_b64_tr_b16 v[228:229], v134 offset:6144
	ds_read_b64_tr_b16 v[230:231], v134 offset:8192
	ds_read_b64_tr_b16 v[232:233], v134 offset:10240
	ds_read_b64_tr_b16 v[234:235], v134 offset:12288
	ds_read_b64_tr_b16 v[236:237], v134 offset:14336
	ds_read_b64_tr_b16 v[238:239], v134 offset:512
	ds_read_b64_tr_b16 v[240:241], v134 offset:2560
	ds_read_b64_tr_b16 v[242:243], v134 offset:4608
	ds_read_b64_tr_b16 v[244:245], v134 offset:6656
	ds_read_b64_tr_b16 v[246:247], v134 offset:8704
	ds_read_b64_tr_b16 v[248:249], v134 offset:10752
	ds_read_b64_tr_b16 v[140:141], v134 offset:12800
	ds_read_b64_tr_b16 v[142:143], v134 offset:14848
	v_mfma_f32_32x32x16_bf16 v[190:205], v[156:159], v[86:89], 0
	v_exp_f32_e32 v48, v48
	v_add_f32_e32 v133, v133, v32
	v_exp_f32_e32 v49, v49
	v_add_f32_e32 v135, v135, v33
	v_exp_f32_e32 v50, v50
	v_mfma_f32_32x32x16_bf16 v[206:221], v[160:163], v[86:89], 0
	v_add_f32_e32 v133, v133, v34
	v_exp_f32_e32 v51, v51
	v_add_f32_e32 v135, v135, v35
	v_exp_f32_e32 v52, v52
	v_add_f32_e32 v133, v133, v36
	v_mfma_f32_32x32x16_bf16 v[190:205], v[164:167], v[82:85], v[190:205]
	v_exp_f32_e32 v53, v53
	v_add_f32_e32 v135, v135, v37
	v_exp_f32_e32 v54, v54
	v_add_f32_e32 v133, v133, v38
	v_exp_f32_e32 v55, v55
	v_add_f32_e32 v135, v135, v39
	v_mfma_f32_32x32x16_bf16 v[206:221], v[168:171], v[82:85], v[206:221]
	v_exp_f32_e32 v56, v56
	v_add_f32_e32 v133, v133, v40
	v_exp_f32_e32 v57, v57
	v_add_f32_e32 v135, v135, v41
	v_exp_f32_e32 v58, v58
	v_mfma_f32_32x32x16_bf16 v[190:205], v[172:175], v[90:93], v[190:205]
	v_add_f32_e32 v133, v133, v42
	v_exp_f32_e32 v59, v59
	v_add_f32_e32 v135, v135, v43
	v_exp_f32_e32 v60, v60
	v_add_f32_e32 v133, v133, v44
	v_mfma_f32_32x32x16_bf16 v[206:221], v[176:179], v[90:93], v[206:221]
	v_exp_f32_e32 v61, v61
	v_add_f32_e32 v135, v135, v45
	v_exp_f32_e32 v62, v62
	v_add_f32_e32 v133, v133, v46
	v_exp_f32_e32 v63, v63
	v_add_f32_e32 v135, v135, v47
	v_mfma_f32_32x32x16_bf16 v[190:205], v[180:183], v[94:97], v[190:205]
	v_add_f32_e32 v133, v133, v48
	v_add_f32_e32 v135, v135, v49
	v_add_f32_e32 v133, v133, v50
	v_add_f32_e32 v135, v135, v51
	v_add_f32_e32 v133, v133, v52
	v_mfma_f32_32x32x16_bf16 v[206:221], v[184:187], v[94:97], v[206:221]
	v_add_f32_e32 v135, v135, v53
	v_add_f32_e32 v133, v133, v54
	v_add_f32_e32 v135, v135, v55
	v_add_f32_e32 v133, v133, v56
	v_add_f32_e32 v135, v135, v57
	v_mfma_f32_32x32x16_bf16 v[190:205], v[64:67], v[98:101], v[190:205]
	v_add_f32_e32 v133, v133, v58
	v_add_f32_e32 v135, v135, v59
	v_add_f32_e32 v133, v133, v60
	v_add_f32_e32 v135, v135, v61
	v_add_f32_e32 v133, v133, v62
	v_add_f32_e32 v135, v135, v63
	v_mfma_f32_32x32x16_bf16 v[206:221], v[68:71], v[98:101], v[206:221]
	v_cvt_pk_bf16_f32 v32, v32, v33
	v_cvt_pk_bf16_f32 v33, v34, v35
	v_cvt_pk_bf16_f32 v34, v36, v37
	v_cvt_pk_bf16_f32 v35, v38, v39
	v_cvt_pk_bf16_f32 v36, v40, v41
	v_mfma_f32_32x32x16_bf16 v[190:205], v[72:75], v[102:105], v[190:205]
	v_cvt_pk_bf16_f32 v37, v42, v43
	v_cvt_pk_bf16_f32 v38, v44, v45
	v_cvt_pk_bf16_f32 v39, v46, v47
	v_cvt_pk_bf16_f32 v48, v48, v49
	v_cvt_pk_bf16_f32 v49, v50, v51
	v_mfma_f32_32x32x16_bf16 v[206:221], v[76:79], v[102:105], v[206:221]
	v_cvt_pk_bf16_f32 v50, v52, v53
	v_cvt_pk_bf16_f32 v51, v54, v55
	v_cvt_pk_bf16_f32 v52, v56, v57
	v_cvt_pk_bf16_f32 v53, v58, v59
	v_cvt_pk_bf16_f32 v54, v60, v61
	v_cvt_pk_bf16_f32 v55, v62, v63
	s_waitcnt vmcnt(3) lgkmcnt(0)
	s_barrier
	ds_read_b128 v[156:159], v146 offset:32768
	ds_read_b128 v[160:163], v146 offset:40960
	ds_read_b128 v[164:167], v147 offset:32768
	ds_read_b128 v[168:171], v147 offset:40960
	ds_read_b128 v[172:175], v148 offset:32768
	ds_read_b128 v[176:179], v148 offset:40960
	ds_read_b128 v[180:183], v149 offset:32768
	ds_read_b128 v[184:187], v149 offset:40960
	ds_read_b128 v[64:67], v150 offset:32768
	ds_read_b128 v[68:71], v150 offset:40960
	ds_read_b128 v[72:75], v151 offset:32768
	ds_read_b128 v[76:79], v151 offset:40960
	v_mfma_f32_32x32x16_bf16 v[0:15], v[32:35], v[222:225], v[0:15]
	s_add_i32 m0, s60, 0x4000
	v_exp_f32_e32 v190, v190
	v_exp_f32_e32 v191, v191
	v_mfma_f32_32x32x16_bf16 v[0:15], v[36:39], v[226:229], v[0:15]
	global_load_lds_dwordx4 v124, s[56:57]
	global_load_lds_dwordx4 v126, s[56:57] offset:1024
	v_exp_f32_e32 v192, v192
	v_exp_f32_e32 v193, v193
	v_mfma_f32_32x32x16_bf16 v[0:15], v[48:51], v[230:233], v[0:15]
	s_add_u32 s56, s56, 0x4000
	s_addc_u32 s57, s57, 0
	v_exp_f32_e32 v194, v194
	v_exp_f32_e32 v195, v195
	v_mfma_f32_32x32x16_bf16 v[0:15], v[52:55], v[234:237], v[0:15]
	s_add_i32 m0, s60, 0xc000
	v_exp_f32_e32 v196, v196
	v_exp_f32_e32 v197, v197
	v_mfma_f32_32x32x16_bf16 v[16:31], v[32:35], v[238:241], v[16:31]
	global_load_lds_dwordx4 v128, s[58:59]
	v_exp_f32_e32 v198, v198
	v_exp_f32_e32 v199, v199
	v_mfma_f32_32x32x16_bf16 v[16:31], v[36:39], v[242:245], v[16:31]
	s_add_u32 s58, s58, 0x2000
	s_addc_u32 s59, s59, 0
	v_exp_f32_e32 v200, v200
	v_exp_f32_e32 v201, v201
	v_mfma_f32_32x32x16_bf16 v[16:31], v[48:51], v[246:249], v[16:31]
	v_exp_f32_e32 v202, v202
	v_exp_f32_e32 v203, v203
	v_mfma_f32_32x32x16_bf16 v[16:31], v[52:55], v[140:143], v[16:31]
	v_exp_f32_e32 v204, v204
	v_exp_f32_e32 v205, v205
	s_waitcnt lgkmcnt(0)
	ds_read_b64_tr_b16 v[222:223], v134 offset:16384
	ds_read_b64_tr_b16 v[224:225], v134 offset:18432
	ds_read_b64_tr_b16 v[226:227], v134 offset:20480
	ds_read_b64_tr_b16 v[228:229], v134 offset:22528
	ds_read_b64_tr_b16 v[230:231], v134 offset:24576
	ds_read_b64_tr_b16 v[232:233], v134 offset:26624
	ds_read_b64_tr_b16 v[234:235], v134 offset:28672
	ds_read_b64_tr_b16 v[236:237], v134 offset:30720
	ds_read_b64_tr_b16 v[238:239], v134 offset:16896
	ds_read_b64_tr_b16 v[240:241], v134 offset:18944
	ds_read_b64_tr_b16 v[242:243], v134 offset:20992
	ds_read_b64_tr_b16 v[244:245], v134 offset:23040
	ds_read_b64_tr_b16 v[246:247], v134 offset:25088
	ds_read_b64_tr_b16 v[248:249], v134 offset:27136
	ds_read_b64_tr_b16 v[140:141], v134 offset:29184
	ds_read_b64_tr_b16 v[142:143], v134 offset:31232
	v_mfma_f32_32x32x16_bf16 v[32:47], v[156:159], v[86:89], 0
	v_exp_f32_e32 v206, v206
	v_add_f32_e32 v133, v133, v190
	v_exp_f32_e32 v207, v207
	v_add_f32_e32 v135, v135, v191
	v_exp_f32_e32 v208, v208
	v_mfma_f32_32x32x16_bf16 v[48:63], v[160:163], v[86:89], 0
	v_add_f32_e32 v133, v133, v192
	v_exp_f32_e32 v209, v209
	v_add_f32_e32 v135, v135, v193
	v_exp_f32_e32 v210, v210
	v_add_f32_e32 v133, v133, v194
	v_mfma_f32_32x32x16_bf16 v[32:47], v[164:167], v[82:85], v[32:47]
	v_exp_f32_e32 v211, v211
	v_add_f32_e32 v135, v135, v195
	v_exp_f32_e32 v212, v212
	v_add_f32_e32 v133, v133, v196
	v_exp_f32_e32 v213, v213
	v_add_f32_e32 v135, v135, v197
	v_mfma_f32_32x32x16_bf16 v[48:63], v[168:171], v[82:85], v[48:63]
	v_exp_f32_e32 v214, v214
	v_add_f32_e32 v133, v133, v198
	v_exp_f32_e32 v215, v215
	v_add_f32_e32 v135, v135, v199
	v_exp_f32_e32 v216, v216
	v_mfma_f32_32x32x16_bf16 v[32:47], v[172:175], v[90:93], v[32:47]
	v_add_f32_e32 v133, v133, v200
	v_exp_f32_e32 v217, v217
	v_add_f32_e32 v135, v135, v201
	v_exp_f32_e32 v218, v218
	v_add_f32_e32 v133, v133, v202
	v_mfma_f32_32x32x16_bf16 v[48:63], v[176:179], v[90:93], v[48:63]
	v_exp_f32_e32 v219, v219
	v_add_f32_e32 v135, v135, v203
	v_exp_f32_e32 v220, v220
	v_add_f32_e32 v133, v133, v204
	v_exp_f32_e32 v221, v221
	v_add_f32_e32 v135, v135, v205
	v_mfma_f32_32x32x16_bf16 v[32:47], v[180:183], v[94:97], v[32:47]
	v_add_f32_e32 v133, v133, v206
	v_add_f32_e32 v135, v135, v207
	v_add_f32_e32 v133, v133, v208
	v_add_f32_e32 v135, v135, v209
	v_add_f32_e32 v133, v133, v210
	v_mfma_f32_32x32x16_bf16 v[48:63], v[184:187], v[94:97], v[48:63]
	v_add_f32_e32 v135, v135, v211
	v_add_f32_e32 v133, v133, v212
	v_add_f32_e32 v135, v135, v213
	v_add_f32_e32 v133, v133, v214
	v_add_f32_e32 v135, v135, v215
	v_mfma_f32_32x32x16_bf16 v[32:47], v[64:67], v[98:101], v[32:47]
	v_add_f32_e32 v133, v133, v216
	v_add_f32_e32 v135, v135, v217
	v_add_f32_e32 v133, v133, v218
	v_add_f32_e32 v135, v135, v219
	v_add_f32_e32 v133, v133, v220
	v_add_f32_e32 v135, v135, v221
	v_mfma_f32_32x32x16_bf16 v[48:63], v[68:71], v[98:101], v[48:63]
	v_cvt_pk_bf16_f32 v190, v190, v191
	v_cvt_pk_bf16_f32 v191, v192, v193
	v_cvt_pk_bf16_f32 v192, v194, v195
	v_cvt_pk_bf16_f32 v193, v196, v197
	v_cvt_pk_bf16_f32 v194, v198, v199
	v_mfma_f32_32x32x16_bf16 v[32:47], v[72:75], v[102:105], v[32:47]
	v_cvt_pk_bf16_f32 v195, v200, v201
	v_cvt_pk_bf16_f32 v196, v202, v203
	v_cvt_pk_bf16_f32 v197, v204, v205
	v_cvt_pk_bf16_f32 v206, v206, v207
	v_cvt_pk_bf16_f32 v207, v208, v209
	v_mfma_f32_32x32x16_bf16 v[48:63], v[76:79], v[102:105], v[48:63]
	v_cvt_pk_bf16_f32 v208, v210, v211
	v_cvt_pk_bf16_f32 v209, v212, v213
	v_cvt_pk_bf16_f32 v210, v214, v215
	v_cvt_pk_bf16_f32 v211, v216, v217
	v_cvt_pk_bf16_f32 v212, v218, v219
	v_cvt_pk_bf16_f32 v213, v220, v221
	s_waitcnt vmcnt(3) lgkmcnt(0)
	s_barrier
	ds_read_b128 v[156:159], v146 offset:0
	ds_read_b128 v[160:163], v146 offset:8192
	ds_read_b128 v[164:167], v147 offset:0
	ds_read_b128 v[168:171], v147 offset:8192
	ds_read_b128 v[172:175], v148 offset:0
	ds_read_b128 v[176:179], v148 offset:8192
	ds_read_b128 v[180:183], v149 offset:0
	ds_read_b128 v[184:187], v149 offset:8192
	ds_read_b128 v[64:67], v150 offset:0
	ds_read_b128 v[68:71], v150 offset:8192
	ds_read_b128 v[72:75], v151 offset:0
	ds_read_b128 v[76:79], v151 offset:8192
	v_mfma_f32_32x32x16_bf16 v[0:15], v[190:193], v[222:225], v[0:15]
	s_add_i32 m0, s60, 0x8000
	v_exp_f32_e32 v32, v32
	v_exp_f32_e32 v33, v33
	v_mfma_f32_32x32x16_bf16 v[0:15], v[194:197], v[226:229], v[0:15]
	global_load_lds_dwordx4 v124, s[56:57]
	global_load_lds_dwordx4 v126, s[56:57] offset:1024
	v_exp_f32_e32 v34, v34
	v_exp_f32_e32 v35, v35
	v_mfma_f32_32x32x16_bf16 v[0:15], v[206:209], v[230:233], v[0:15]
	s_add_u32 s56, s56, 0x4000
	s_addc_u32 s57, s57, 0
	v_exp_f32_e32 v36, v36
	v_exp_f32_e32 v37, v37
	v_mfma_f32_32x32x16_bf16 v[0:15], v[210:213], v[234:237], v[0:15]
	s_add_i32 m0, s60, 0x10000
	v_exp_f32_e32 v38, v38
	v_exp_f32_e32 v39, v39
	v_mfma_f32_32x32x16_bf16 v[16:31], v[190:193], v[238:241], v[16:31]
	global_load_lds_dwordx4 v128, s[58:59]
	v_exp_f32_e32 v40, v40
	v_exp_f32_e32 v41, v41
	v_mfma_f32_32x32x16_bf16 v[16:31], v[194:197], v[242:245], v[16:31]
	s_add_u32 s58, s58, 0x2000
	s_addc_u32 s59, s59, 0
	v_exp_f32_e32 v42, v42
	v_exp_f32_e32 v43, v43
	v_mfma_f32_32x32x16_bf16 v[16:31], v[206:209], v[246:249], v[16:31]
	v_exp_f32_e32 v44, v44
	v_exp_f32_e32 v45, v45
	v_mfma_f32_32x32x16_bf16 v[16:31], v[210:213], v[140:143], v[16:31]
	v_exp_f32_e32 v46, v46
	v_exp_f32_e32 v47, v47
	s_waitcnt lgkmcnt(0)
	ds_read_b64_tr_b16 v[222:223], v134 offset:32768
	ds_read_b64_tr_b16 v[224:225], v134 offset:34816
	ds_read_b64_tr_b16 v[226:227], v134 offset:36864
	ds_read_b64_tr_b16 v[228:229], v134 offset:38912
	ds_read_b64_tr_b16 v[230:231], v134 offset:40960
	ds_read_b64_tr_b16 v[232:233], v134 offset:43008
	ds_read_b64_tr_b16 v[234:235], v134 offset:45056
	ds_read_b64_tr_b16 v[236:237], v134 offset:47104
	ds_read_b64_tr_b16 v[238:239], v134 offset:33280
	ds_read_b64_tr_b16 v[240:241], v134 offset:35328
	ds_read_b64_tr_b16 v[242:243], v134 offset:37376
	ds_read_b64_tr_b16 v[244:245], v134 offset:39424
	ds_read_b64_tr_b16 v[246:247], v134 offset:41472
	ds_read_b64_tr_b16 v[248:249], v134 offset:43520
	ds_read_b64_tr_b16 v[140:141], v134 offset:45568
	ds_read_b64_tr_b16 v[142:143], v134 offset:47616
	v_mfma_f32_32x32x16_bf16 v[190:205], v[156:159], v[86:89], 0
	v_exp_f32_e32 v48, v48
	v_add_f32_e32 v133, v133, v32
	v_exp_f32_e32 v49, v49
	v_add_f32_e32 v135, v135, v33
	v_exp_f32_e32 v50, v50
	v_mfma_f32_32x32x16_bf16 v[206:221], v[160:163], v[86:89], 0
	v_add_f32_e32 v133, v133, v34
	v_exp_f32_e32 v51, v51
	v_add_f32_e32 v135, v135, v35
	v_exp_f32_e32 v52, v52
	v_add_f32_e32 v133, v133, v36
	v_mfma_f32_32x32x16_bf16 v[190:205], v[164:167], v[82:85], v[190:205]
	v_exp_f32_e32 v53, v53
	v_add_f32_e32 v135, v135, v37
	v_exp_f32_e32 v54, v54
	v_add_f32_e32 v133, v133, v38
	v_exp_f32_e32 v55, v55
	v_add_f32_e32 v135, v135, v39
	v_mfma_f32_32x32x16_bf16 v[206:221], v[168:171], v[82:85], v[206:221]
	v_exp_f32_e32 v56, v56
	v_add_f32_e32 v133, v133, v40
	v_exp_f32_e32 v57, v57
	v_add_f32_e32 v135, v135, v41
	v_exp_f32_e32 v58, v58
	v_mfma_f32_32x32x16_bf16 v[190:205], v[172:175], v[90:93], v[190:205]
	v_add_f32_e32 v133, v133, v42
	v_exp_f32_e32 v59, v59
	v_add_f32_e32 v135, v135, v43
	v_exp_f32_e32 v60, v60
	v_add_f32_e32 v133, v133, v44
	v_mfma_f32_32x32x16_bf16 v[206:221], v[176:179], v[90:93], v[206:221]
	v_exp_f32_e32 v61, v61
	v_add_f32_e32 v135, v135, v45
	v_exp_f32_e32 v62, v62
	v_add_f32_e32 v133, v133, v46
	v_exp_f32_e32 v63, v63
	v_add_f32_e32 v135, v135, v47
	v_mfma_f32_32x32x16_bf16 v[190:205], v[180:183], v[94:97], v[190:205]
	v_add_f32_e32 v133, v133, v48
	v_add_f32_e32 v135, v135, v49
	v_add_f32_e32 v133, v133, v50
	v_add_f32_e32 v135, v135, v51
	v_add_f32_e32 v133, v133, v52
	v_mfma_f32_32x32x16_bf16 v[206:221], v[184:187], v[94:97], v[206:221]
	v_add_f32_e32 v135, v135, v53
	v_add_f32_e32 v133, v133, v54
	v_add_f32_e32 v135, v135, v55
	v_add_f32_e32 v133, v133, v56
	v_add_f32_e32 v135, v135, v57
	v_mfma_f32_32x32x16_bf16 v[190:205], v[64:67], v[98:101], v[190:205]
	v_add_f32_e32 v133, v133, v58
	v_add_f32_e32 v135, v135, v59
	v_add_f32_e32 v133, v133, v60
	v_add_f32_e32 v135, v135, v61
	v_add_f32_e32 v133, v133, v62
	v_add_f32_e32 v135, v135, v63
	v_mfma_f32_32x32x16_bf16 v[206:221], v[68:71], v[98:101], v[206:221]
	v_cvt_pk_bf16_f32 v32, v32, v33
	v_cvt_pk_bf16_f32 v33, v34, v35
	v_cvt_pk_bf16_f32 v34, v36, v37
	v_cvt_pk_bf16_f32 v35, v38, v39
	v_cvt_pk_bf16_f32 v36, v40, v41
	v_mfma_f32_32x32x16_bf16 v[190:205], v[72:75], v[102:105], v[190:205]
	v_cvt_pk_bf16_f32 v37, v42, v43
	v_cvt_pk_bf16_f32 v38, v44, v45
	v_cvt_pk_bf16_f32 v39, v46, v47
	v_cvt_pk_bf16_f32 v48, v48, v49
	v_cvt_pk_bf16_f32 v49, v50, v51
	v_mfma_f32_32x32x16_bf16 v[206:221], v[76:79], v[102:105], v[206:221]
	v_cvt_pk_bf16_f32 v50, v52, v53
	v_cvt_pk_bf16_f32 v51, v54, v55
	v_cvt_pk_bf16_f32 v52, v56, v57
	v_cvt_pk_bf16_f32 v53, v58, v59
	v_cvt_pk_bf16_f32 v54, v60, v61
	v_cvt_pk_bf16_f32 v55, v62, v63
	s_waitcnt vmcnt(3) lgkmcnt(0)
	s_barrier
	ds_read_b128 v[156:159], v146 offset:16384
	ds_read_b128 v[160:163], v146 offset:24576
	ds_read_b128 v[164:167], v147 offset:16384
	ds_read_b128 v[168:171], v147 offset:24576
	ds_read_b128 v[172:175], v148 offset:16384
	ds_read_b128 v[176:179], v148 offset:24576
	ds_read_b128 v[180:183], v149 offset:16384
	ds_read_b128 v[184:187], v149 offset:24576
	ds_read_b128 v[64:67], v150 offset:16384
	ds_read_b128 v[68:71], v150 offset:24576
	ds_read_b128 v[72:75], v151 offset:16384
	ds_read_b128 v[76:79], v151 offset:24576
	v_mfma_f32_32x32x16_bf16 v[0:15], v[32:35], v[222:225], v[0:15]
	s_add_i32 m0, s60, 0x0
	v_exp_f32_e32 v190, v190
	v_exp_f32_e32 v191, v191
	v_mfma_f32_32x32x16_bf16 v[0:15], v[36:39], v[226:229], v[0:15]
	global_load_lds_dwordx4 v124, s[56:57]
	global_load_lds_dwordx4 v126, s[56:57] offset:1024
	v_exp_f32_e32 v192, v192
	v_exp_f32_e32 v193, v193
	v_mfma_f32_32x32x16_bf16 v[0:15], v[48:51], v[230:233], v[0:15]
	s_add_u32 s56, s56, 0x4000
	s_addc_u32 s57, s57, 0
	v_exp_f32_e32 v194, v194
	v_exp_f32_e32 v195, v195
	v_mfma_f32_32x32x16_bf16 v[0:15], v[52:55], v[234:237], v[0:15]
	s_add_i32 m0, s60, 0x14000
	v_exp_f32_e32 v196, v196
	v_exp_f32_e32 v197, v197
	v_mfma_f32_32x32x16_bf16 v[16:31], v[32:35], v[238:241], v[16:31]
	global_load_lds_dwordx4 v128, s[58:59]
	v_exp_f32_e32 v198, v198
	v_exp_f32_e32 v199, v199
	v_mfma_f32_32x32x16_bf16 v[16:31], v[36:39], v[242:245], v[16:31]
	s_add_u32 s58, s58, 0x2000
	s_addc_u32 s59, s59, 0
	v_exp_f32_e32 v200, v200
	v_exp_f32_e32 v201, v201
	v_mfma_f32_32x32x16_bf16 v[16:31], v[48:51], v[246:249], v[16:31]
	v_exp_f32_e32 v202, v202
	v_exp_f32_e32 v203, v203
	v_mfma_f32_32x32x16_bf16 v[16:31], v[52:55], v[140:143], v[16:31]
	v_exp_f32_e32 v204, v204
	v_exp_f32_e32 v205, v205
	s_waitcnt lgkmcnt(0)
	ds_read_b64_tr_b16 v[222:223], v134 offset:0
	ds_read_b64_tr_b16 v[224:225], v134 offset:2048
	ds_read_b64_tr_b16 v[226:227], v134 offset:4096
	ds_read_b64_tr_b16 v[228:229], v134 offset:6144
	ds_read_b64_tr_b16 v[230:231], v134 offset:8192
	ds_read_b64_tr_b16 v[232:233], v134 offset:10240
	ds_read_b64_tr_b16 v[234:235], v134 offset:12288
	ds_read_b64_tr_b16 v[236:237], v134 offset:14336
	ds_read_b64_tr_b16 v[238:239], v134 offset:512
	ds_read_b64_tr_b16 v[240:241], v134 offset:2560
	ds_read_b64_tr_b16 v[242:243], v134 offset:4608
	ds_read_b64_tr_b16 v[244:245], v134 offset:6656
	ds_read_b64_tr_b16 v[246:247], v134 offset:8704
	ds_read_b64_tr_b16 v[248:249], v134 offset:10752
	ds_read_b64_tr_b16 v[140:141], v134 offset:12800
	ds_read_b64_tr_b16 v[142:143], v134 offset:14848
	v_mfma_f32_32x32x16_bf16 v[32:47], v[156:159], v[86:89], 0
	v_exp_f32_e32 v206, v206
	v_add_f32_e32 v133, v133, v190
	v_exp_f32_e32 v207, v207
	v_add_f32_e32 v135, v135, v191
	v_exp_f32_e32 v208, v208
	v_mfma_f32_32x32x16_bf16 v[48:63], v[160:163], v[86:89], 0
	v_add_f32_e32 v133, v133, v192
	v_exp_f32_e32 v209, v209
	v_add_f32_e32 v135, v135, v193
	v_exp_f32_e32 v210, v210
	v_add_f32_e32 v133, v133, v194
	v_mfma_f32_32x32x16_bf16 v[32:47], v[164:167], v[82:85], v[32:47]
	v_exp_f32_e32 v211, v211
	v_add_f32_e32 v135, v135, v195
	v_exp_f32_e32 v212, v212
	v_add_f32_e32 v133, v133, v196
	v_exp_f32_e32 v213, v213
	v_add_f32_e32 v135, v135, v197
	v_mfma_f32_32x32x16_bf16 v[48:63], v[168:171], v[82:85], v[48:63]
	v_exp_f32_e32 v214, v214
	v_add_f32_e32 v133, v133, v198
	v_exp_f32_e32 v215, v215
	v_add_f32_e32 v135, v135, v199
	v_exp_f32_e32 v216, v216
	v_mfma_f32_32x32x16_bf16 v[32:47], v[172:175], v[90:93], v[32:47]
	v_add_f32_e32 v133, v133, v200
	v_exp_f32_e32 v217, v217
	v_add_f32_e32 v135, v135, v201
	v_exp_f32_e32 v218, v218
	v_add_f32_e32 v133, v133, v202
	v_mfma_f32_32x32x16_bf16 v[48:63], v[176:179], v[90:93], v[48:63]
	v_exp_f32_e32 v219, v219
	v_add_f32_e32 v135, v135, v203
	v_exp_f32_e32 v220, v220
	v_add_f32_e32 v133, v133, v204
	v_exp_f32_e32 v221, v221
	v_add_f32_e32 v135, v135, v205
	v_mfma_f32_32x32x16_bf16 v[32:47], v[180:183], v[94:97], v[32:47]
	v_add_f32_e32 v133, v133, v206
	v_add_f32_e32 v135, v135, v207
	v_add_f32_e32 v133, v133, v208
	v_add_f32_e32 v135, v135, v209
	v_add_f32_e32 v133, v133, v210
	v_mfma_f32_32x32x16_bf16 v[48:63], v[184:187], v[94:97], v[48:63]
	v_add_f32_e32 v135, v135, v211
	v_add_f32_e32 v133, v133, v212
	v_add_f32_e32 v135, v135, v213
	v_add_f32_e32 v133, v133, v214
	v_add_f32_e32 v135, v135, v215
	v_mfma_f32_32x32x16_bf16 v[32:47], v[64:67], v[98:101], v[32:47]
	v_add_f32_e32 v133, v133, v216
	v_add_f32_e32 v135, v135, v217
	v_add_f32_e32 v133, v133, v218
	v_add_f32_e32 v135, v135, v219
	v_add_f32_e32 v133, v133, v220
	v_add_f32_e32 v135, v135, v221
	v_mfma_f32_32x32x16_bf16 v[48:63], v[68:71], v[98:101], v[48:63]
	v_cvt_pk_bf16_f32 v190, v190, v191
	v_cvt_pk_bf16_f32 v191, v192, v193
	v_cvt_pk_bf16_f32 v192, v194, v195
	v_cvt_pk_bf16_f32 v193, v196, v197
	v_cvt_pk_bf16_f32 v194, v198, v199
	v_mfma_f32_32x32x16_bf16 v[32:47], v[72:75], v[102:105], v[32:47]
	v_cvt_pk_bf16_f32 v195, v200, v201
	v_cvt_pk_bf16_f32 v196, v202, v203
	v_cvt_pk_bf16_f32 v197, v204, v205
	v_cvt_pk_bf16_f32 v206, v206, v207
	v_cvt_pk_bf16_f32 v207, v208, v209
	v_mfma_f32_32x32x16_bf16 v[48:63], v[76:79], v[102:105], v[48:63]
	v_cvt_pk_bf16_f32 v208, v210, v211
	v_cvt_pk_bf16_f32 v209, v212, v213
	v_cvt_pk_bf16_f32 v210, v214, v215
	v_cvt_pk_bf16_f32 v211, v216, v217
	v_cvt_pk_bf16_f32 v212, v218, v219
	v_cvt_pk_bf16_f32 v213, v220, v221
	s_waitcnt vmcnt(3) lgkmcnt(0)
	s_barrier
	ds_read_b128 v[156:159], v146 offset:32768
	ds_read_b128 v[160:163], v146 offset:40960
	ds_read_b128 v[164:167], v147 offset:32768
	ds_read_b128 v[168:171], v147 offset:40960
	ds_read_b128 v[172:175], v148 offset:32768
	ds_read_b128 v[176:179], v148 offset:40960
	ds_read_b128 v[180:183], v149 offset:32768
	ds_read_b128 v[184:187], v149 offset:40960
	ds_read_b128 v[64:67], v150 offset:32768
	ds_read_b128 v[68:71], v150 offset:40960
	ds_read_b128 v[72:75], v151 offset:32768
	ds_read_b128 v[76:79], v151 offset:40960
	v_mfma_f32_32x32x16_bf16 v[0:15], v[190:193], v[222:225], v[0:15]
	s_add_i32 m0, s60, 0x4000
	v_exp_f32_e32 v32, v32
	v_exp_f32_e32 v33, v33
	v_mfma_f32_32x32x16_bf16 v[0:15], v[194:197], v[226:229], v[0:15]
	global_load_lds_dwordx4 v124, s[56:57]
	global_load_lds_dwordx4 v126, s[56:57] offset:1024
	v_exp_f32_e32 v34, v34
	v_exp_f32_e32 v35, v35
	v_mfma_f32_32x32x16_bf16 v[0:15], v[206:209], v[230:233], v[0:15]
	s_add_u32 s56, s56, 0x4000
	s_addc_u32 s57, s57, 0
	v_exp_f32_e32 v36, v36
	v_exp_f32_e32 v37, v37
	v_mfma_f32_32x32x16_bf16 v[0:15], v[210:213], v[234:237], v[0:15]
	s_add_i32 m0, s60, 0xc000
	v_exp_f32_e32 v38, v38
	v_exp_f32_e32 v39, v39
	v_mfma_f32_32x32x16_bf16 v[16:31], v[190:193], v[238:241], v[16:31]
	global_load_lds_dwordx4 v128, s[58:59]
	v_exp_f32_e32 v40, v40
	v_exp_f32_e32 v41, v41
	v_mfma_f32_32x32x16_bf16 v[16:31], v[194:197], v[242:245], v[16:31]
	s_add_u32 s58, s58, 0x2000
	s_addc_u32 s59, s59, 0
	v_exp_f32_e32 v42, v42
	v_exp_f32_e32 v43, v43
	v_mfma_f32_32x32x16_bf16 v[16:31], v[206:209], v[246:249], v[16:31]
	v_exp_f32_e32 v44, v44
	v_exp_f32_e32 v45, v45
	v_mfma_f32_32x32x16_bf16 v[16:31], v[210:213], v[140:143], v[16:31]
	v_exp_f32_e32 v46, v46
	v_exp_f32_e32 v47, v47
	s_waitcnt lgkmcnt(0)
	ds_read_b64_tr_b16 v[222:223], v134 offset:16384
	ds_read_b64_tr_b16 v[224:225], v134 offset:18432
	ds_read_b64_tr_b16 v[226:227], v134 offset:20480
	ds_read_b64_tr_b16 v[228:229], v134 offset:22528
	ds_read_b64_tr_b16 v[230:231], v134 offset:24576
	ds_read_b64_tr_b16 v[232:233], v134 offset:26624
	ds_read_b64_tr_b16 v[234:235], v134 offset:28672
	ds_read_b64_tr_b16 v[236:237], v134 offset:30720
	ds_read_b64_tr_b16 v[238:239], v134 offset:16896
	ds_read_b64_tr_b16 v[240:241], v134 offset:18944
	ds_read_b64_tr_b16 v[242:243], v134 offset:20992
	ds_read_b64_tr_b16 v[244:245], v134 offset:23040
	ds_read_b64_tr_b16 v[246:247], v134 offset:25088
	ds_read_b64_tr_b16 v[248:249], v134 offset:27136
	ds_read_b64_tr_b16 v[140:141], v134 offset:29184
	ds_read_b64_tr_b16 v[142:143], v134 offset:31232
	v_mfma_f32_32x32x16_bf16 v[190:205], v[156:159], v[86:89], 0
	v_exp_f32_e32 v48, v48
	v_add_f32_e32 v133, v133, v32
	v_exp_f32_e32 v49, v49
	v_add_f32_e32 v135, v135, v33
	v_exp_f32_e32 v50, v50
	v_mfma_f32_32x32x16_bf16 v[206:221], v[160:163], v[86:89], 0
	v_add_f32_e32 v133, v133, v34
	v_exp_f32_e32 v51, v51
	v_add_f32_e32 v135, v135, v35
	v_exp_f32_e32 v52, v52
	v_add_f32_e32 v133, v133, v36
	v_mfma_f32_32x32x16_bf16 v[190:205], v[164:167], v[82:85], v[190:205]
	v_exp_f32_e32 v53, v53
	v_add_f32_e32 v135, v135, v37
	v_exp_f32_e32 v54, v54
	v_add_f32_e32 v133, v133, v38
	v_exp_f32_e32 v55, v55
	v_add_f32_e32 v135, v135, v39
	v_mfma_f32_32x32x16_bf16 v[206:221], v[168:171], v[82:85], v[206:221]
	v_exp_f32_e32 v56, v56
	v_add_f32_e32 v133, v133, v40
	v_exp_f32_e32 v57, v57
	v_add_f32_e32 v135, v135, v41
	v_exp_f32_e32 v58, v58
	v_mfma_f32_32x32x16_bf16 v[190:205], v[172:175], v[90:93], v[190:205]
	v_add_f32_e32 v133, v133, v42
	v_exp_f32_e32 v59, v59
	v_add_f32_e32 v135, v135, v43
	v_exp_f32_e32 v60, v60
	v_add_f32_e32 v133, v133, v44
	v_mfma_f32_32x32x16_bf16 v[206:221], v[176:179], v[90:93], v[206:221]
	v_exp_f32_e32 v61, v61
	v_add_f32_e32 v135, v135, v45
	v_exp_f32_e32 v62, v62
	v_add_f32_e32 v133, v133, v46
	v_exp_f32_e32 v63, v63
	v_add_f32_e32 v135, v135, v47
	v_mfma_f32_32x32x16_bf16 v[190:205], v[180:183], v[94:97], v[190:205]
	v_add_f32_e32 v133, v133, v48
	v_add_f32_e32 v135, v135, v49
	v_add_f32_e32 v133, v133, v50
	v_add_f32_e32 v135, v135, v51
	v_add_f32_e32 v133, v133, v52
	v_mfma_f32_32x32x16_bf16 v[206:221], v[184:187], v[94:97], v[206:221]
	v_add_f32_e32 v135, v135, v53
	v_add_f32_e32 v133, v133, v54
	v_add_f32_e32 v135, v135, v55
	v_add_f32_e32 v133, v133, v56
	v_add_f32_e32 v135, v135, v57
	v_mfma_f32_32x32x16_bf16 v[190:205], v[64:67], v[98:101], v[190:205]
	v_add_f32_e32 v133, v133, v58
	v_add_f32_e32 v135, v135, v59
	v_add_f32_e32 v133, v133, v60
	v_add_f32_e32 v135, v135, v61
	v_add_f32_e32 v133, v133, v62
	v_add_f32_e32 v135, v135, v63
	v_mfma_f32_32x32x16_bf16 v[206:221], v[68:71], v[98:101], v[206:221]
	v_cvt_pk_bf16_f32 v32, v32, v33
	v_cvt_pk_bf16_f32 v33, v34, v35
	v_cvt_pk_bf16_f32 v34, v36, v37
	v_cvt_pk_bf16_f32 v35, v38, v39
	v_cvt_pk_bf16_f32 v36, v40, v41
	v_mfma_f32_32x32x16_bf16 v[190:205], v[72:75], v[102:105], v[190:205]
	v_cvt_pk_bf16_f32 v37, v42, v43
	v_cvt_pk_bf16_f32 v38, v44, v45
	v_cvt_pk_bf16_f32 v39, v46, v47
	v_cvt_pk_bf16_f32 v48, v48, v49
	v_cvt_pk_bf16_f32 v49, v50, v51
	v_mfma_f32_32x32x16_bf16 v[206:221], v[76:79], v[102:105], v[206:221]
	v_cvt_pk_bf16_f32 v50, v52, v53
	v_cvt_pk_bf16_f32 v51, v54, v55
	v_cvt_pk_bf16_f32 v52, v56, v57
	v_cvt_pk_bf16_f32 v53, v58, v59
	v_cvt_pk_bf16_f32 v54, v60, v61
	v_cvt_pk_bf16_f32 v55, v62, v63
	s_waitcnt vmcnt(3) lgkmcnt(0)
	s_barrier
	ds_read_b128 v[156:159], v146 offset:0
	ds_read_b128 v[160:163], v146 offset:8192
	ds_read_b128 v[164:167], v147 offset:0
	ds_read_b128 v[168:171], v147 offset:8192
	ds_read_b128 v[172:175], v148 offset:0
	ds_read_b128 v[176:179], v148 offset:8192
	ds_read_b128 v[180:183], v149 offset:0
	ds_read_b128 v[184:187], v149 offset:8192
	ds_read_b128 v[64:67], v150 offset:0
	ds_read_b128 v[68:71], v150 offset:8192
	ds_read_b128 v[72:75], v151 offset:0
	ds_read_b128 v[76:79], v151 offset:8192
	v_mfma_f32_32x32x16_bf16 v[0:15], v[32:35], v[222:225], v[0:15]
	s_add_i32 m0, s60, 0x10000
	v_exp_f32_e32 v190, v190
	v_exp_f32_e32 v191, v191
	v_mfma_f32_32x32x16_bf16 v[0:15], v[36:39], v[226:229], v[0:15]
	global_load_lds_dwordx4 v128, s[58:59]
	v_exp_f32_e32 v192, v192
	v_exp_f32_e32 v193, v193
	v_mfma_f32_32x32x16_bf16 v[0:15], v[48:51], v[230:233], v[0:15]
	s_add_u32 s58, s58, 0x2000
	s_addc_u32 s59, s59, 0
	v_exp_f32_e32 v194, v194
	v_exp_f32_e32 v195, v195
	v_mfma_f32_32x32x16_bf16 v[0:15], v[52:55], v[234:237], v[0:15]
	v_exp_f32_e32 v196, v196
	v_exp_f32_e32 v197, v197
	v_mfma_f32_32x32x16_bf16 v[16:31], v[32:35], v[238:241], v[16:31]
	v_exp_f32_e32 v198, v198
	v_exp_f32_e32 v199, v199
	v_mfma_f32_32x32x16_bf16 v[16:31], v[36:39], v[242:245], v[16:31]
	v_exp_f32_e32 v200, v200
	v_exp_f32_e32 v201, v201
	v_mfma_f32_32x32x16_bf16 v[16:31], v[48:51], v[246:249], v[16:31]
	v_exp_f32_e32 v202, v202
	v_exp_f32_e32 v203, v203
	v_mfma_f32_32x32x16_bf16 v[16:31], v[52:55], v[140:143], v[16:31]
	v_exp_f32_e32 v204, v204
	v_exp_f32_e32 v205, v205
	s_waitcnt lgkmcnt(0)
	ds_read_b64_tr_b16 v[222:223], v134 offset:32768
	ds_read_b64_tr_b16 v[224:225], v134 offset:34816
	ds_read_b64_tr_b16 v[226:227], v134 offset:36864
	ds_read_b64_tr_b16 v[228:229], v134 offset:38912
	ds_read_b64_tr_b16 v[230:231], v134 offset:40960
	ds_read_b64_tr_b16 v[232:233], v134 offset:43008
	ds_read_b64_tr_b16 v[234:235], v134 offset:45056
	ds_read_b64_tr_b16 v[236:237], v134 offset:47104
	ds_read_b64_tr_b16 v[238:239], v134 offset:33280
	ds_read_b64_tr_b16 v[240:241], v134 offset:35328
	ds_read_b64_tr_b16 v[242:243], v134 offset:37376
	ds_read_b64_tr_b16 v[244:245], v134 offset:39424
	ds_read_b64_tr_b16 v[246:247], v134 offset:41472
	ds_read_b64_tr_b16 v[248:249], v134 offset:43520
	ds_read_b64_tr_b16 v[140:141], v134 offset:45568
	ds_read_b64_tr_b16 v[142:143], v134 offset:47616
	v_mfma_f32_32x32x16_bf16 v[32:47], v[156:159], v[86:89], 0
	v_exp_f32_e32 v206, v206
	v_add_f32_e32 v133, v133, v190
	v_exp_f32_e32 v207, v207
	v_add_f32_e32 v135, v135, v191
	v_exp_f32_e32 v208, v208
	v_mfma_f32_32x32x16_bf16 v[48:63], v[160:163], v[86:89], 0
	v_add_f32_e32 v133, v133, v192
	v_exp_f32_e32 v209, v209
	v_add_f32_e32 v135, v135, v193
	v_exp_f32_e32 v210, v210
	v_add_f32_e32 v133, v133, v194
	v_mfma_f32_32x32x16_bf16 v[32:47], v[164:167], v[82:85], v[32:47]
	v_exp_f32_e32 v211, v211
	v_add_f32_e32 v135, v135, v195
	v_exp_f32_e32 v212, v212
	v_add_f32_e32 v133, v133, v196
	v_exp_f32_e32 v213, v213
	v_add_f32_e32 v135, v135, v197
	v_mfma_f32_32x32x16_bf16 v[48:63], v[168:171], v[82:85], v[48:63]
	v_exp_f32_e32 v214, v214
	v_add_f32_e32 v133, v133, v198
	v_exp_f32_e32 v215, v215
	v_add_f32_e32 v135, v135, v199
	v_exp_f32_e32 v216, v216
	v_mfma_f32_32x32x16_bf16 v[32:47], v[172:175], v[90:93], v[32:47]
	v_add_f32_e32 v133, v133, v200
	v_exp_f32_e32 v217, v217
	v_add_f32_e32 v135, v135, v201
	v_exp_f32_e32 v218, v218
	v_add_f32_e32 v133, v133, v202
	v_mfma_f32_32x32x16_bf16 v[48:63], v[176:179], v[90:93], v[48:63]
	v_exp_f32_e32 v219, v219
	v_add_f32_e32 v135, v135, v203
	v_exp_f32_e32 v220, v220
	v_add_f32_e32 v133, v133, v204
	v_exp_f32_e32 v221, v221
	v_add_f32_e32 v135, v135, v205
	v_mfma_f32_32x32x16_bf16 v[32:47], v[180:183], v[94:97], v[32:47]
	v_add_f32_e32 v133, v133, v206
	v_add_f32_e32 v135, v135, v207
	v_add_f32_e32 v133, v133, v208
	v_add_f32_e32 v135, v135, v209
	v_add_f32_e32 v133, v133, v210
	v_mfma_f32_32x32x16_bf16 v[48:63], v[184:187], v[94:97], v[48:63]
	v_add_f32_e32 v135, v135, v211
	v_add_f32_e32 v133, v133, v212
	v_add_f32_e32 v135, v135, v213
	v_add_f32_e32 v133, v133, v214
	v_add_f32_e32 v135, v135, v215
	v_mfma_f32_32x32x16_bf16 v[32:47], v[64:67], v[98:101], v[32:47]
	v_add_f32_e32 v133, v133, v216
	v_add_f32_e32 v135, v135, v217
	v_add_f32_e32 v133, v133, v218
	v_add_f32_e32 v135, v135, v219
	v_add_f32_e32 v133, v133, v220
	v_add_f32_e32 v135, v135, v221
	v_mfma_f32_32x32x16_bf16 v[48:63], v[68:71], v[98:101], v[48:63]
	v_cvt_pk_bf16_f32 v190, v190, v191
	v_cvt_pk_bf16_f32 v191, v192, v193
	v_cvt_pk_bf16_f32 v192, v194, v195
	v_cvt_pk_bf16_f32 v193, v196, v197
	v_cvt_pk_bf16_f32 v194, v198, v199
	v_mfma_f32_32x32x16_bf16 v[32:47], v[72:75], v[102:105], v[32:47]
	v_cvt_pk_bf16_f32 v195, v200, v201
	v_cvt_pk_bf16_f32 v196, v202, v203
	v_cvt_pk_bf16_f32 v197, v204, v205
	v_cvt_pk_bf16_f32 v206, v206, v207
	v_cvt_pk_bf16_f32 v207, v208, v209
	v_mfma_f32_32x32x16_bf16 v[48:63], v[76:79], v[102:105], v[48:63]
	v_cvt_pk_bf16_f32 v208, v210, v211
	v_cvt_pk_bf16_f32 v209, v212, v213
	v_cvt_pk_bf16_f32 v210, v214, v215
	v_cvt_pk_bf16_f32 v211, v216, v217
	v_cvt_pk_bf16_f32 v212, v218, v219
	v_cvt_pk_bf16_f32 v213, v220, v221
	s_waitcnt vmcnt(1) lgkmcnt(0)
	s_barrier
	ds_read_b128 v[156:159], v146 offset:16384
	ds_read_b128 v[160:163], v146 offset:24576
	ds_read_b128 v[164:167], v147 offset:16384
	ds_read_b128 v[168:171], v147 offset:24576
	ds_read_b128 v[172:175], v148 offset:16384
	ds_read_b128 v[176:179], v148 offset:24576
	ds_read_b128 v[180:183], v149 offset:16384
	ds_read_b128 v[184:187], v149 offset:24576
	ds_read_b128 v[64:67], v150 offset:16384
	ds_read_b128 v[68:71], v150 offset:24576
	ds_read_b128 v[72:75], v151 offset:16384
	ds_read_b128 v[76:79], v151 offset:24576
	v_mfma_f32_32x32x16_bf16 v[0:15], v[190:193], v[222:225], v[0:15]
	v_exp_f32_e32 v32, v32
	v_exp_f32_e32 v33, v33
	v_mfma_f32_32x32x16_bf16 v[0:15], v[194:197], v[226:229], v[0:15]
	v_exp_f32_e32 v34, v34
	v_exp_f32_e32 v35, v35
	v_mfma_f32_32x32x16_bf16 v[0:15], v[206:209], v[230:233], v[0:15]
	v_exp_f32_e32 v36, v36
	v_exp_f32_e32 v37, v37
	v_mfma_f32_32x32x16_bf16 v[0:15], v[210:213], v[234:237], v[0:15]
	v_exp_f32_e32 v38, v38
	v_exp_f32_e32 v39, v39
	v_mfma_f32_32x32x16_bf16 v[16:31], v[190:193], v[238:241], v[16:31]
	v_exp_f32_e32 v40, v40
	v_exp_f32_e32 v41, v41
	v_mfma_f32_32x32x16_bf16 v[16:31], v[194:197], v[242:245], v[16:31]
	v_exp_f32_e32 v42, v42
	v_exp_f32_e32 v43, v43
	v_mfma_f32_32x32x16_bf16 v[16:31], v[206:209], v[246:249], v[16:31]
	v_exp_f32_e32 v44, v44
	v_exp_f32_e32 v45, v45
	v_mfma_f32_32x32x16_bf16 v[16:31], v[210:213], v[140:143], v[16:31]
	v_exp_f32_e32 v46, v46
	v_exp_f32_e32 v47, v47
	s_waitcnt lgkmcnt(0)
	ds_read_b64_tr_b16 v[222:223], v134 offset:0
	ds_read_b64_tr_b16 v[224:225], v134 offset:2048
	ds_read_b64_tr_b16 v[226:227], v134 offset:4096
	ds_read_b64_tr_b16 v[228:229], v134 offset:6144
	ds_read_b64_tr_b16 v[230:231], v134 offset:8192
	ds_read_b64_tr_b16 v[232:233], v134 offset:10240
	ds_read_b64_tr_b16 v[234:235], v134 offset:12288
	ds_read_b64_tr_b16 v[236:237], v134 offset:14336
	ds_read_b64_tr_b16 v[238:239], v134 offset:512
	ds_read_b64_tr_b16 v[240:241], v134 offset:2560
	ds_read_b64_tr_b16 v[242:243], v134 offset:4608
	ds_read_b64_tr_b16 v[244:245], v134 offset:6656
	ds_read_b64_tr_b16 v[246:247], v134 offset:8704
	ds_read_b64_tr_b16 v[248:249], v134 offset:10752
	ds_read_b64_tr_b16 v[140:141], v134 offset:12800
	ds_read_b64_tr_b16 v[142:143], v134 offset:14848
	v_mfma_f32_32x32x16_bf16 v[190:205], v[156:159], v[86:89], 0
	v_exp_f32_e32 v48, v48
	v_add_f32_e32 v133, v133, v32
	v_exp_f32_e32 v49, v49
	v_add_f32_e32 v135, v135, v33
	v_exp_f32_e32 v50, v50
	v_mfma_f32_32x32x16_bf16 v[206:221], v[160:163], v[86:89], 0
	v_add_f32_e32 v133, v133, v34
	v_exp_f32_e32 v51, v51
	v_add_f32_e32 v135, v135, v35
	v_exp_f32_e32 v52, v52
	v_add_f32_e32 v133, v133, v36
	v_mfma_f32_32x32x16_bf16 v[190:205], v[164:167], v[82:85], v[190:205]
	v_exp_f32_e32 v53, v53
	v_add_f32_e32 v135, v135, v37
	v_exp_f32_e32 v54, v54
	v_add_f32_e32 v133, v133, v38
	v_exp_f32_e32 v55, v55
	v_add_f32_e32 v135, v135, v39
	v_mfma_f32_32x32x16_bf16 v[206:221], v[168:171], v[82:85], v[206:221]
	v_exp_f32_e32 v56, v56
	v_add_f32_e32 v133, v133, v40
	v_exp_f32_e32 v57, v57
	v_add_f32_e32 v135, v135, v41
	v_exp_f32_e32 v58, v58
	v_mfma_f32_32x32x16_bf16 v[190:205], v[172:175], v[90:93], v[190:205]
	v_add_f32_e32 v133, v133, v42
	v_exp_f32_e32 v59, v59
	v_add_f32_e32 v135, v135, v43
	v_exp_f32_e32 v60, v60
	v_add_f32_e32 v133, v133, v44
	v_mfma_f32_32x32x16_bf16 v[206:221], v[176:179], v[90:93], v[206:221]
	v_exp_f32_e32 v61, v61
	v_add_f32_e32 v135, v135, v45
	v_exp_f32_e32 v62, v62
	v_add_f32_e32 v133, v133, v46
	v_exp_f32_e32 v63, v63
	v_add_f32_e32 v135, v135, v47
	v_mfma_f32_32x32x16_bf16 v[190:205], v[180:183], v[94:97], v[190:205]
	v_add_f32_e32 v133, v133, v48
	v_add_f32_e32 v135, v135, v49
	v_add_f32_e32 v133, v133, v50
	v_add_f32_e32 v135, v135, v51
	v_add_f32_e32 v133, v133, v52
	v_mfma_f32_32x32x16_bf16 v[206:221], v[184:187], v[94:97], v[206:221]
	v_add_f32_e32 v135, v135, v53
	v_add_f32_e32 v133, v133, v54
	v_add_f32_e32 v135, v135, v55
	v_add_f32_e32 v133, v133, v56
	v_add_f32_e32 v135, v135, v57
	v_mfma_f32_32x32x16_bf16 v[190:205], v[64:67], v[98:101], v[190:205]
	v_add_f32_e32 v133, v133, v58
	v_add_f32_e32 v135, v135, v59
	v_add_f32_e32 v133, v133, v60
	v_add_f32_e32 v135, v135, v61
	v_add_f32_e32 v133, v133, v62
	v_add_f32_e32 v135, v135, v63
	v_mfma_f32_32x32x16_bf16 v[206:221], v[68:71], v[98:101], v[206:221]
	v_cvt_pk_bf16_f32 v32, v32, v33
	v_cvt_pk_bf16_f32 v33, v34, v35
	v_cvt_pk_bf16_f32 v34, v36, v37
	v_cvt_pk_bf16_f32 v35, v38, v39
	v_cvt_pk_bf16_f32 v36, v40, v41
	v_mfma_f32_32x32x16_bf16 v[190:205], v[72:75], v[102:105], v[190:205]
	v_cvt_pk_bf16_f32 v37, v42, v43
	v_cvt_pk_bf16_f32 v38, v44, v45
	v_cvt_pk_bf16_f32 v39, v46, v47
	v_cvt_pk_bf16_f32 v48, v48, v49
	v_cvt_pk_bf16_f32 v49, v50, v51
	v_mfma_f32_32x32x16_bf16 v[206:221], v[76:79], v[102:105], v[206:221]
	v_cvt_pk_bf16_f32 v50, v52, v53
	v_cvt_pk_bf16_f32 v51, v54, v55
	v_cvt_pk_bf16_f32 v52, v56, v57
	v_cvt_pk_bf16_f32 v53, v58, v59
	v_cvt_pk_bf16_f32 v54, v60, v61
	v_cvt_pk_bf16_f32 v55, v62, v63
	s_waitcnt vmcnt(0) lgkmcnt(0)
	s_barrier
	s_nop 7
	s_nop 3
	v_mfma_f32_32x32x16_bf16 v[0:15], v[32:35], v[222:225], v[0:15]
	v_exp_f32_e32 v190, v190
	v_exp_f32_e32 v191, v191
	v_mfma_f32_32x32x16_bf16 v[0:15], v[36:39], v[226:229], v[0:15]
	v_exp_f32_e32 v192, v192
	v_exp_f32_e32 v193, v193
	v_mfma_f32_32x32x16_bf16 v[0:15], v[48:51], v[230:233], v[0:15]
	v_exp_f32_e32 v194, v194
	v_exp_f32_e32 v195, v195
	v_mfma_f32_32x32x16_bf16 v[0:15], v[52:55], v[234:237], v[0:15]
	v_exp_f32_e32 v196, v196
	v_exp_f32_e32 v197, v197
	v_mfma_f32_32x32x16_bf16 v[16:31], v[32:35], v[238:241], v[16:31]
	v_exp_f32_e32 v198, v198
	v_exp_f32_e32 v199, v199
	v_mfma_f32_32x32x16_bf16 v[16:31], v[36:39], v[242:245], v[16:31]
	v_exp_f32_e32 v200, v200
	v_exp_f32_e32 v201, v201
	v_mfma_f32_32x32x16_bf16 v[16:31], v[48:51], v[246:249], v[16:31]
	v_exp_f32_e32 v202, v202
	v_exp_f32_e32 v203, v203
	v_mfma_f32_32x32x16_bf16 v[16:31], v[52:55], v[140:143], v[16:31]
	v_exp_f32_e32 v204, v204
	v_exp_f32_e32 v205, v205
	s_waitcnt lgkmcnt(0)
	ds_read_b64_tr_b16 v[222:223], v134 offset:16384
	ds_read_b64_tr_b16 v[224:225], v134 offset:18432
	ds_read_b64_tr_b16 v[226:227], v134 offset:20480
	ds_read_b64_tr_b16 v[228:229], v134 offset:22528
	ds_read_b64_tr_b16 v[230:231], v134 offset:24576
	ds_read_b64_tr_b16 v[232:233], v134 offset:26624
	ds_read_b64_tr_b16 v[234:235], v134 offset:28672
	ds_read_b64_tr_b16 v[236:237], v134 offset:30720
	ds_read_b64_tr_b16 v[238:239], v134 offset:16896
	ds_read_b64_tr_b16 v[240:241], v134 offset:18944
	ds_read_b64_tr_b16 v[242:243], v134 offset:20992
	ds_read_b64_tr_b16 v[244:245], v134 offset:23040
	ds_read_b64_tr_b16 v[246:247], v134 offset:25088
	ds_read_b64_tr_b16 v[248:249], v134 offset:27136
	ds_read_b64_tr_b16 v[140:141], v134 offset:29184
	ds_read_b64_tr_b16 v[142:143], v134 offset:31232
	s_nop 3
	v_exp_f32_e32 v206, v206
	v_add_f32_e32 v133, v133, v190
	v_exp_f32_e32 v207, v207
	v_add_f32_e32 v135, v135, v191
	v_exp_f32_e32 v208, v208
	v_add_f32_e32 v133, v133, v192
	v_exp_f32_e32 v209, v209
	v_add_f32_e32 v135, v135, v193
	v_exp_f32_e32 v210, v210
	v_add_f32_e32 v133, v133, v194
	v_exp_f32_e32 v211, v211
	v_add_f32_e32 v135, v135, v195
	v_exp_f32_e32 v212, v212
	v_add_f32_e32 v133, v133, v196
	v_exp_f32_e32 v213, v213
	v_add_f32_e32 v135, v135, v197
	v_exp_f32_e32 v214, v214
	v_add_f32_e32 v133, v133, v198
	v_exp_f32_e32 v215, v215
	v_add_f32_e32 v135, v135, v199
	v_exp_f32_e32 v216, v216
	v_add_f32_e32 v133, v133, v200
	v_exp_f32_e32 v217, v217
	v_add_f32_e32 v135, v135, v201
	v_exp_f32_e32 v218, v218
	v_add_f32_e32 v133, v133, v202
	v_exp_f32_e32 v219, v219
	v_add_f32_e32 v135, v135, v203
	v_exp_f32_e32 v220, v220
	v_add_f32_e32 v133, v133, v204
	v_exp_f32_e32 v221, v221
	v_add_f32_e32 v135, v135, v205
	v_add_f32_e32 v133, v133, v206
	v_add_f32_e32 v135, v135, v207
	v_add_f32_e32 v133, v133, v208
	v_add_f32_e32 v135, v135, v209
	v_add_f32_e32 v133, v133, v210
	v_add_f32_e32 v135, v135, v211
	v_add_f32_e32 v133, v133, v212
	v_add_f32_e32 v135, v135, v213
	v_add_f32_e32 v133, v133, v214
	v_add_f32_e32 v135, v135, v215
	v_add_f32_e32 v133, v133, v216
	v_add_f32_e32 v135, v135, v217
	v_add_f32_e32 v133, v133, v218
	v_add_f32_e32 v135, v135, v219
	v_add_f32_e32 v133, v133, v220
	v_add_f32_e32 v135, v135, v221
	v_cvt_pk_bf16_f32 v190, v190, v191
	v_cvt_pk_bf16_f32 v191, v192, v193
	v_cvt_pk_bf16_f32 v192, v194, v195
	v_cvt_pk_bf16_f32 v193, v196, v197
	v_cvt_pk_bf16_f32 v194, v198, v199
	v_cvt_pk_bf16_f32 v195, v200, v201
	v_cvt_pk_bf16_f32 v196, v202, v203
	v_cvt_pk_bf16_f32 v197, v204, v205
	v_cvt_pk_bf16_f32 v206, v206, v207
	v_cvt_pk_bf16_f32 v207, v208, v209
	v_cvt_pk_bf16_f32 v208, v210, v211
	v_cvt_pk_bf16_f32 v209, v212, v213
	v_cvt_pk_bf16_f32 v210, v214, v215
	v_cvt_pk_bf16_f32 v211, v216, v217
	v_cvt_pk_bf16_f32 v212, v218, v219
	v_cvt_pk_bf16_f32 v213, v220, v221
	s_waitcnt lgkmcnt(0)
	s_nop 7
	s_nop 3
	v_mfma_f32_32x32x16_bf16 v[0:15], v[190:193], v[222:225], v[0:15]
	v_mfma_f32_32x32x16_bf16 v[0:15], v[194:197], v[226:229], v[0:15]
	v_mfma_f32_32x32x16_bf16 v[0:15], v[206:209], v[230:233], v[0:15]
	v_mfma_f32_32x32x16_bf16 v[0:15], v[210:213], v[234:237], v[0:15]
	v_mfma_f32_32x32x16_bf16 v[16:31], v[190:193], v[238:241], v[16:31]
	v_mfma_f32_32x32x16_bf16 v[16:31], v[194:197], v[242:245], v[16:31]
	v_mfma_f32_32x32x16_bf16 v[16:31], v[206:209], v[246:249], v[16:31]
	v_mfma_f32_32x32x16_bf16 v[16:31], v[210:213], v[140:143], v[16:31]
	v_add_f32_e32 v32, v133, v135
	s_nop 0
	v_mov_b32_e32 v33, v32
	s_nop 1
	v_permlane32_swap_b32_e32 v32, v33
	s_and_saveexec_b64 s[4:5], s[6:7]
	v_add_f32_e32 v32, v32, v33
	ds_write_b32 v153, v32
	s_or_b64 exec, exec, s[4:5]
	s_waitcnt lgkmcnt(0)
	v_add_u32_e32 v40, v113, v117
	ds_read_b128 v[32:35], v40
	ds_read_b128 v[36:39], v40 offset:32
	s_waitcnt lgkmcnt(1)
	v_rcp_f32_e32 v41, v32
	v_rcp_f32_e32 v42, v33
	v_rcp_f32_e32 v43, v34
	v_rcp_f32_e32 v44, v35
	ds_read_b128 v[32:35], v40 offset:64
	s_waitcnt lgkmcnt(1)
	v_rcp_f32_e32 v45, v36
	v_rcp_f32_e32 v46, v37
	v_rcp_f32_e32 v47, v38
	v_rcp_f32_e32 v48, v39
	ds_read_b128 v[36:39], v40 offset:96
	s_waitcnt lgkmcnt(1)
	v_rcp_f32_e32 v40, v32
	v_rcp_f32_e32 v49, v33
	v_lshlrev_b32_e32 v32, 1, v116
	v_mov_b32_e32 v33, v81
	v_rcp_f32_e32 v50, v34
	v_rcp_f32_e32 v51, v35
	v_lshl_add_u64 v[32:33], s[38:39], 0, v[32:33]
	v_lshlrev_b32_e32 v34, 1, v108
	v_mov_b32_e32 v35, v81
	v_lshl_add_u64 v[32:33], v[32:33], 0, v[34:35]
	v_mul_f32_e32 v0, v0, v41
	v_lshl_add_u64 v[32:33], v[32:33], 0, v[118:119]
	v_cvt_pk_bf16_f32 v0, v0, v81
	global_store_short v[32:33], v0, off
	v_mul_f32_e32 v0, v16, v41
	v_cvt_pk_bf16_f32 v0, v0, v81
	global_store_short v[32:33], v0, off offset:64
	v_mul_f32_e32 v0, v1, v42
	v_cvt_pk_bf16_f32 v0, v0, v81
	global_store_short v[32:33], v0, off offset:2048
	v_mul_f32_e32 v0, v17, v42
	v_cvt_pk_bf16_f32 v0, v0, v81
	global_store_short v[32:33], v0, off offset:2112
	v_mul_f32_e32 v0, v2, v43
	v_cvt_pk_bf16_f32 v2, v0, v81
	v_add_co_u32_e32 v0, vcc, s47, v32
	s_waitcnt lgkmcnt(0)
	v_rcp_f32_e32 v36, v36
	v_addc_co_u32_e32 v1, vcc, 0, v33, vcc
	global_store_short v[0:1], v2, off
	v_mul_f32_e32 v2, v18, v43
	v_cvt_pk_bf16_f32 v2, v2, v81
	global_store_short v[0:1], v2, off offset:64
	v_mul_f32_e32 v2, v3, v44
	v_cvt_pk_bf16_f32 v2, v2, v81
	global_store_short v[0:1], v2, off offset:2048
	v_mul_f32_e32 v2, v19, v44
	v_cvt_pk_bf16_f32 v2, v2, v81
	global_store_short v[0:1], v2, off offset:2112
	v_mul_f32_e32 v0, v4, v45
	v_cvt_pk_bf16_f32 v4, v0, v81
	v_add_co_u32_e32 v0, vcc, s41, v32
	v_rcp_f32_e32 v37, v37
	s_nop 0
	v_addc_co_u32_e32 v1, vcc, 0, v33, vcc
	v_add_co_u32_e32 v2, vcc, s48, v32
	v_rcp_f32_e32 v38, v38
	s_nop 0
	v_addc_co_u32_e32 v3, vcc, 0, v33, vcc
	global_store_short v[2:3], v4, off offset:-4096
	v_mul_f32_e32 v4, v20, v45
	v_cvt_pk_bf16_f32 v4, v4, v81
	global_store_short v[0:1], v4, off offset:64
	v_mul_f32_e32 v4, v5, v46
	v_cvt_pk_bf16_f32 v4, v4, v81
	global_store_short v[0:1], v4, off offset:2048
	v_mul_f32_e32 v4, v21, v46
	v_cvt_pk_bf16_f32 v4, v4, v81
	global_store_short v[0:1], v4, off offset:2112
	v_mul_f32_e32 v0, v6, v47
	v_cvt_pk_bf16_f32 v0, v0, v81
	global_store_short v[2:3], v0, off
	v_mul_f32_e32 v0, v22, v47
	v_cvt_pk_bf16_f32 v0, v0, v81
	global_store_short v[2:3], v0, off offset:64
	v_mul_f32_e32 v0, v7, v48
	v_cvt_pk_bf16_f32 v0, v0, v81
	global_store_short v[2:3], v0, off offset:2048
	v_mul_f32_e32 v0, v23, v48
	v_cvt_pk_bf16_f32 v0, v0, v81
	global_store_short v[2:3], v0, off offset:2112
	v_mul_f32_e32 v0, v8, v40
	v_cvt_pk_bf16_f32 v4, v0, v81
	v_add_co_u32_e32 v0, vcc, s49, v32
	v_rcp_f32_e32 v39, v39
	s_nop 0
	v_addc_co_u32_e32 v1, vcc, 0, v33, vcc
	v_add_co_u32_e32 v2, vcc, s54, v32
	s_nop 1
	v_addc_co_u32_e32 v3, vcc, 0, v33, vcc
	global_store_short v[2:3], v4, off offset:-4096
	v_mul_f32_e32 v4, v24, v40
	v_cvt_pk_bf16_f32 v4, v4, v81
	global_store_short v[0:1], v4, off offset:64
	v_mul_f32_e32 v4, v9, v49
	v_cvt_pk_bf16_f32 v4, v4, v81
	global_store_short v[0:1], v4, off offset:2048
	v_mul_f32_e32 v4, v25, v49
	v_cvt_pk_bf16_f32 v4, v4, v81
	global_store_short v[0:1], v4, off offset:2112
	v_mul_f32_e32 v0, v10, v50
	v_cvt_pk_bf16_f32 v0, v0, v81
	global_store_short v[2:3], v0, off
	v_mul_f32_e32 v0, v26, v50
	v_cvt_pk_bf16_f32 v0, v0, v81
	global_store_short v[2:3], v0, off offset:64
	v_mul_f32_e32 v0, v11, v51
	v_cvt_pk_bf16_f32 v0, v0, v81
	global_store_short v[2:3], v0, off offset:2048
	v_mul_f32_e32 v0, v27, v51
	v_cvt_pk_bf16_f32 v0, v0, v81
	global_store_short v[2:3], v0, off offset:2112
	v_mul_f32_e32 v0, v12, v36
	v_cvt_pk_bf16_f32 v4, v0, v81
	v_add_co_u32_e32 v0, vcc, s45, v32
	s_nop 1
	v_addc_co_u32_e32 v1, vcc, 0, v33, vcc
	v_add_co_u32_e32 v2, vcc, s55, v32
	s_nop 1
	v_addc_co_u32_e32 v3, vcc, 0, v33, vcc
	global_store_short v[2:3], v4, off offset:-4096
	v_mul_f32_e32 v4, v28, v36
	v_cvt_pk_bf16_f32 v4, v4, v81
	global_store_short v[0:1], v4, off offset:64
	v_mul_f32_e32 v4, v13, v37
	v_cvt_pk_bf16_f32 v4, v4, v81
	global_store_short v[0:1], v4, off offset:2048
	v_mul_f32_e32 v4, v29, v37
	v_cvt_pk_bf16_f32 v4, v4, v81
	global_store_short v[0:1], v4, off offset:2112
	v_mul_f32_e32 v0, v14, v38
	v_cvt_pk_bf16_f32 v0, v0, v81
	global_store_short v[2:3], v0, off
	v_mul_f32_e32 v0, v30, v38
	v_cvt_pk_bf16_f32 v0, v0, v81
	global_store_short v[2:3], v0, off offset:64
	v_mul_f32_e32 v0, v15, v39
	v_cvt_pk_bf16_f32 v0, v0, v81
	global_store_short v[2:3], v0, off offset:2048
	v_mul_f32_e32 v0, v31, v39
	v_cvt_pk_bf16_f32 v0, v0, v81
	global_store_short v[2:3], v0, off offset:2112
	s_barrier
	s_branch .LBB0_1590
